# all 16 K-loop LDS-DMA per iteration now saddr form (no 64-bit VGPR address math left in the loops)
# speedup vs baseline: 1.0042x; 1.0042x over previous
; #define PG8_STAGE(bufoff, gbase, voff) do { _Pragma("unroll") for (int _i = 0; _i < 2; ++_i) \
;         __builtin_amdgcn_global_load_lds((const unsigned*)((const char*)(gbase) + (voff)[_i]), (PG8_LAS unsigned*)(lds + (bufoff) + ldsw + _i * 8192), 16, 0, 0); } while (0)
; #define PG8_LDA(dst, b, h) do { _Pragma("unroll") for (int m = 0; m < 4; ++m) _Pragma("unroll") for (int k = 0; k < 2; ++k) dst[m][k] = *(const PG8_LAS bf16x8*)(lds + PG8_SA(b, h) + aoff + m * 2048 + k * 1024); } while (0)
; #define PG8_LDB(dst, b, h) do { _Pragma("unroll") for (int n = 0; n < 2; ++n) _Pragma("unroll") for (int k = 0; k < 2; ++k) dst[n][k] = *(const PG8_LAS bf16x8*)(lds + PG8_SB(b, h) + boff + n * 2048 + k * 1024); } while (0)
; #define PG8_MMA(ai, bj, At, Bt) do { __builtin_amdgcn_s_setprio(1); _Pragma("unroll") for (int m = 0; m < 4; ++m) _Pragma("unroll") for (int n = 0; n < 2; ++n) _Pragma("unroll") for (int k = 0; k < 2; ++k) \
;         acc[ai][bj][m][n] = __builtin_amdgcn_mfma_f32_16x16x32_bf16(Bt[n][k], At[m][k], acc[ai][bj][m][n], 0, 0, 0); __builtin_amdgcn_s_setprio(0); } while (0)
; #define PG8_WAIT_V(n) asm volatile("s_waitcnt vmcnt(" #n ")" ::: "memory")
; #define PG8_WAIT_L(n) asm volatile("s_waitcnt lgkmcnt(" #n ")" ::: "memory")
; #define PG8_BAR __builtin_amdgcn_s_barrier()
; #define PG8_SCHED __builtin_amdgcn_sched_barrier(0)
; template <class Epi, class Sched, bool ALIGN_EPI = false, bool SP2 = false>
; __device__ __forceinline__ void gemm_phase(PG8_LAS unsigned char* lds, const Gemm g, const Sched& S, const Epi& E) {
;     ...
;             PG8_LDB(B0, 0, 0); PG8_LDB(B1, 0, 1); PG8_SCHED; PG8_LDA(At, 0, 0); PG8_STAGE(PG8_SA(1, 1), a1 + hstep, voffA);
;             PG8_WAIT_V(8); PG8_WAIT_L(0); PG8_BAR; PG8_MMA(0, 0, At, B0); PG8_MMA(0, 1, At, B1); PG8_BAR; PG8_SCHED;
;             PG8_LDA(At, 0, 1); PG8_STAGE(PG8_SB(0, 0), b2, voffB); PG8_STAGE(PG8_SB(0, 1), b2 + hstep, voffB); PG8_STAGE(PG8_SA(0, 0), a2, voffA);
;             PG8_WAIT_V(8); PG8_WAIT_L(0); PG8_BAR; PG8_MMA(1, 0, At, B0); PG8_MMA(1, 1, At, B1); PG8_BAR; PG8_SCHED;
.LBB0_180:
	s_add_u32 s36, s34, 0xfff00000
	s_addc_u32 s37, s35, -1
	s_mov_b32 m0, s45
	s_nop 0
	global_load_lds_dwordx4 v138, s[36:37]
	s_mov_b32 m0, s46
	s_nop 0
	global_load_lds_dwordx4 v142, s[36:37]
	s_add_u32 s36, s36, 0x80
	s_addc_u32 s37, s37, 0
	ds_read_b128 v[130:133], v170
	ds_read_b128 v[134:137], v170 offset:1024
	ds_read_b128 v[178:181], v170 offset:2048
	ds_read_b128 v[182:185], v170 offset:3072
	ds_read_b128 v[186:189], v171
	ds_read_b128 v[190:193], v171 offset:1024
	ds_read_b128 v[194:197], v171 offset:2048
	ds_read_b128 v[200:203], v171 offset:3072
	s_cmp_eq_u32 s56, 60
	s_cselect_b32 s39, s7, s37
	s_cselect_b32 s38, s25, s36
	s_cselect_b32 s37, s15, s55
	s_cselect_b32 s36, s31, s54
	s_add_i32 m0, s40, 0xc000
	ds_read_b128 v[204:207], v172
	ds_read_b128 v[208:211], v172 offset:1024
	ds_read_b128 v[212:215], v172 offset:2048
	ds_read_b128 v[216:219], v172 offset:3072
	ds_read_b128 v[220:223], v172 offset:4096
	ds_read_b128 v[224:227], v172 offset:5120
	ds_read_b128 v[228:231], v172 offset:6144
	ds_read_b128 v[232:235], v172 offset:7168
	global_load_lds_dwordx4 v148, s[34:35]
	s_add_i32 m0, s40, 0xe000
	s_nop 0
	global_load_lds_dwordx4 v150, s[34:35]
	s_waitcnt vmcnt(8)
	s_waitcnt lgkmcnt(0)
	s_barrier
	v_mfma_f32_16x16x32_bf16 v[126:129], v[130:133], v[204:207], v[126:129]
	v_mfma_f32_16x16x32_bf16 v[122:125], v[178:181], v[204:207], v[122:125]
	v_mfma_f32_16x16x32_bf16 v[110:113], v[130:133], v[212:215], v[110:113]
	v_mfma_f32_16x16x32_bf16 v[106:109], v[178:181], v[212:215], v[106:109]
	v_mfma_f32_16x16x32_bf16 v[94:97], v[130:133], v[220:223], v[94:97]
	v_mfma_f32_16x16x32_bf16 v[90:93], v[178:181], v[220:223], v[90:93]
	v_mfma_f32_16x16x32_bf16 v[78:81], v[130:133], v[228:231], v[78:81]
	v_mfma_f32_16x16x32_bf16 v[74:77], v[178:181], v[228:231], v[74:77]
	v_mfma_f32_16x16x32_bf16 v[126:129], v[134:137], v[208:211], v[126:129]
	v_mfma_f32_16x16x32_bf16 v[122:125], v[182:185], v[208:211], v[122:125]
	v_mfma_f32_16x16x32_bf16 v[110:113], v[134:137], v[216:219], v[110:113]
	v_mfma_f32_16x16x32_bf16 v[106:109], v[182:185], v[216:219], v[106:109]
	v_mfma_f32_16x16x32_bf16 v[94:97], v[134:137], v[224:227], v[94:97]
	v_mfma_f32_16x16x32_bf16 v[90:93], v[182:185], v[224:227], v[90:93]
	v_mfma_f32_16x16x32_bf16 v[78:81], v[134:137], v[232:235], v[78:81]
	v_mfma_f32_16x16x32_bf16 v[74:77], v[182:185], v[232:235], v[74:77]
	v_mfma_f32_16x16x32_bf16 v[118:121], v[186:189], v[204:207], v[118:121]
	v_mfma_f32_16x16x32_bf16 v[114:117], v[194:197], v[204:207], v[114:117]
	v_mfma_f32_16x16x32_bf16 v[102:105], v[186:189], v[212:215], v[102:105]
	v_mfma_f32_16x16x32_bf16 v[98:101], v[194:197], v[212:215], v[98:101]
	v_mfma_f32_16x16x32_bf16 v[86:89], v[186:189], v[220:223], v[86:89]
	v_mfma_f32_16x16x32_bf16 v[82:85], v[194:197], v[220:223], v[82:85]
	v_mfma_f32_16x16x32_bf16 v[70:73], v[186:189], v[228:231], v[70:73]
	v_mfma_f32_16x16x32_bf16 v[66:69], v[194:197], v[228:231], v[66:69]
	v_mfma_f32_16x16x32_bf16 v[118:121], v[190:193], v[208:211], v[118:121]
	v_mfma_f32_16x16x32_bf16 v[114:117], v[200:203], v[208:211], v[114:117]
	v_mfma_f32_16x16x32_bf16 v[102:105], v[190:193], v[216:219], v[102:105]
	v_mfma_f32_16x16x32_bf16 v[98:101], v[200:203], v[216:219], v[98:101]
	v_mfma_f32_16x16x32_bf16 v[86:89], v[190:193], v[224:227], v[86:89]
	v_mfma_f32_16x16x32_bf16 v[82:85], v[200:203], v[224:227], v[82:85]
	v_mfma_f32_16x16x32_bf16 v[70:73], v[190:193], v[232:235], v[70:73]
	v_mfma_f32_16x16x32_bf16 v[66:69], v[200:203], v[232:235], v[66:69]
	s_barrier
	s_add_i32 s57, s49, s33
	s_mov_b32 m0, s57
	ds_read_b128 v[204:207], v172 offset:16384
	ds_read_b128 v[208:211], v172 offset:17408
	ds_read_b128 v[212:215], v172 offset:18432
	ds_read_b128 v[216:219], v172 offset:19456
	ds_read_b128 v[220:223], v172 offset:20480
	ds_read_b128 v[224:227], v172 offset:21504
	ds_read_b128 v[228:231], v172 offset:22528
	ds_read_b128 v[232:235], v172 offset:23552
	global_load_lds_dwordx4 v140, s[36:37]
	s_add_i32 m0, s57, 0x2000
	s_add_u32 s58, s36, 0x100000
	s_addc_u32 s59, s37, 0
	s_add_i32 s57, s50, s33
	global_load_lds_dwordx4 v144, s[36:37]
	s_mov_b32 m0, s57
	s_nop 0
	global_load_lds_dwordx4 v140, s[58:59]
	s_add_i32 m0, s57, 0x2000
	s_nop 0
	global_load_lds_dwordx4 v144, s[58:59]
	s_waitcnt vmcnt(6)
	s_waitcnt lgkmcnt(0)
	s_barrier
	v_mfma_f32_16x16x32_bf16 v[62:65], v[130:133], v[204:207], v[62:65]
	v_mfma_f32_16x16x32_bf16 v[58:61], v[178:181], v[204:207], v[58:61]
	v_mfma_f32_16x16x32_bf16 v[46:49], v[130:133], v[212:215], v[46:49]
	v_mfma_f32_16x16x32_bf16 v[42:45], v[178:181], v[212:215], v[42:45]
	v_mfma_f32_16x16x32_bf16 v[30:33], v[130:133], v[220:223], v[30:33]
	v_mfma_f32_16x16x32_bf16 v[26:29], v[178:181], v[220:223], v[26:29]
	v_mfma_f32_16x16x32_bf16 v[14:17], v[130:133], v[228:231], v[14:17]
	v_mfma_f32_16x16x32_bf16 v[10:13], v[178:181], v[228:231], v[10:13]
	v_mfma_f32_16x16x32_bf16 v[62:65], v[134:137], v[208:211], v[62:65]
	v_mfma_f32_16x16x32_bf16 v[58:61], v[182:185], v[208:211], v[58:61]
	v_mfma_f32_16x16x32_bf16 v[46:49], v[134:137], v[216:219], v[46:49]
	v_mfma_f32_16x16x32_bf16 v[42:45], v[182:185], v[216:219], v[42:45]
	v_mfma_f32_16x16x32_bf16 v[30:33], v[134:137], v[224:227], v[30:33]
	v_mfma_f32_16x16x32_bf16 v[26:29], v[182:185], v[224:227], v[26:29]
	v_mfma_f32_16x16x32_bf16 v[14:17], v[134:137], v[232:235], v[14:17]
	v_mfma_f32_16x16x32_bf16 v[10:13], v[182:185], v[232:235], v[10:13]
	v_mfma_f32_16x16x32_bf16 v[54:57], v[186:189], v[204:207], v[54:57]
	v_mfma_f32_16x16x32_bf16 v[50:53], v[194:197], v[204:207], v[50:53]
	v_mfma_f32_16x16x32_bf16 v[38:41], v[186:189], v[212:215], v[38:41]
	v_mfma_f32_16x16x32_bf16 v[34:37], v[194:197], v[212:215], v[34:37]
	v_mfma_f32_16x16x32_bf16 v[22:25], v[186:189], v[220:223], v[22:25]
	v_mfma_f32_16x16x32_bf16 v[18:21], v[194:197], v[220:223], v[18:21]
	v_mfma_f32_16x16x32_bf16 v[6:9], v[186:189], v[228:231], v[6:9]
	v_mfma_f32_16x16x32_bf16 v[2:5], v[194:197], v[228:231], v[2:5]
	v_mfma_f32_16x16x32_bf16 v[54:57], v[190:193], v[208:211], v[54:57]
	v_mfma_f32_16x16x32_bf16 v[50:53], v[200:203], v[208:211], v[50:53]
	v_mfma_f32_16x16x32_bf16 v[38:41], v[190:193], v[216:219], v[38:41]
	v_mfma_f32_16x16x32_bf16 v[34:37], v[200:203], v[216:219], v[34:37]
	v_mfma_f32_16x16x32_bf16 v[22:25], v[190:193], v[224:227], v[22:25]
	v_mfma_f32_16x16x32_bf16 v[18:21], v[200:203], v[224:227], v[18:21]
	v_mfma_f32_16x16x32_bf16 v[6:9], v[190:193], v[232:235], v[6:9]
	v_mfma_f32_16x16x32_bf16 v[2:5], v[200:203], v[232:235], v[2:5]
	s_barrier
; #define PG8_STAGE(bufoff, gbase, voff) do { _Pragma("unroll") for (int _i = 0; _i < 2; ++_i) \
;         __builtin_amdgcn_global_load_lds((const unsigned*)((const char*)(gbase) + (voff)[_i]), (PG8_LAS unsigned*)(lds + (bufoff) + ldsw + _i * 8192), 16, 0, 0); } while (0)
; #define PG8_LDA(dst, b, h) do { _Pragma("unroll") for (int m = 0; m < 4; ++m) _Pragma("unroll") for (int k = 0; k < 2; ++k) dst[m][k] = *(const PG8_LAS bf16x8*)(lds + PG8_SA(b, h) + aoff + m * 2048 + k * 1024); } while (0)
; #define PG8_LDB(dst, b, h) do { _Pragma("unroll") for (int n = 0; n < 2; ++n) _Pragma("unroll") for (int k = 0; k < 2; ++k) dst[n][k] = *(const PG8_LAS bf16x8*)(lds + PG8_SB(b, h) + boff + n * 2048 + k * 1024); } while (0)
; #define PG8_MMA(ai, bj, At, Bt) do { __builtin_amdgcn_s_setprio(1); _Pragma("unroll") for (int m = 0; m < 4; ++m) _Pragma("unroll") for (int n = 0; n < 2; ++n) _Pragma("unroll") for (int k = 0; k < 2; ++k) \
;         acc[ai][bj][m][n] = __builtin_amdgcn_mfma_f32_16x16x32_bf16(Bt[n][k], At[m][k], acc[ai][bj][m][n], 0, 0, 0); __builtin_amdgcn_s_setprio(0); } while (0)
; #define PG8_WAIT_V(n) asm volatile("s_waitcnt vmcnt(" #n ")" ::: "memory")
; #define PG8_WAIT_L(n) asm volatile("s_waitcnt lgkmcnt(" #n ")" ::: "memory")
; #define PG8_BAR __builtin_amdgcn_s_barrier()
; #define PG8_SCHED __builtin_amdgcn_sched_barrier(0)
; template <class Epi, class Sched, bool ALIGN_EPI = false, bool SP2 = false>
; __device__ __forceinline__ void gemm_phase(PG8_LAS unsigned char* lds, const Gemm g, const Sched& S, const Epi& E) {
;     ...
;         for (int t = 0; t < nt; t += 2) {
;             const bool last = (t == nt - 2);
;             const char* a1 = cA + (size_t)(t + 1) * kstep;
;             const char* a2 = last ? nA : cA + (size_t)(t + 2) * kstep; const char* b2 = last ? nB : cB + (size_t)(t + 2) * kstep;
;     ...
;             PG8_LDB(B0, 1, 0); PG8_LDB(B1, 1, 1); PG8_SCHED; PG8_LDA(At, 1, 0); PG8_STAGE(PG8_SA(0, 1), a2 + hstep, voffA);
;             PG8_WAIT_V(8); PG8_WAIT_L(0); PG8_BAR; PG8_MMA(0, 0, At, B0); PG8_MMA(0, 1, At, B1); PG8_BAR; PG8_SCHED;
;             PG8_LDA(At, 1, 1); PG8_STAGE(PG8_SB(1, 0), b3, voffB); PG8_STAGE(PG8_SB(1, 1), b3 + hstep, voffB); PG8_STAGE(PG8_SA(1, 0), a3, voffA);
;             PG8_WAIT_V(8); PG8_WAIT_L(0); PG8_BAR; PG8_MMA(1, 0, At, B0); PG8_MMA(1, 1, At, B1); PG8_BAR; PG8_SCHED;
	s_mov_b32 m0, s40
	s_nop 0
	global_load_lds_dwordx4 v138, s[38:39]
	s_mov_b32 m0, s41
	s_nop 0
	global_load_lds_dwordx4 v142, s[38:39]
	s_add_i32 s57, 0, 0x18000
	v_add_u32_e32 v146, s57, v159
	s_add_i32 s58, 0, 0x1c000
	ds_read_b128 v[130:133], v146
	ds_read_b128 v[134:137], v146 offset:1024
	ds_read_b128 v[178:181], v146 offset:2048
	ds_read_b128 v[182:185], v146 offset:3072
	v_add_u32_e32 v146, s58, v159
	ds_read_b128 v[186:189], v146
	ds_read_b128 v[190:193], v146 offset:1024
	ds_read_b128 v[194:197], v146 offset:2048
	ds_read_b128 v[200:203], v146 offset:3072
	s_add_u32 s38, s38, 0x100000
	s_addc_u32 s39, s39, 0
	s_mov_b32 m0, s42
	ds_read_b128 v[204:207], v172 offset:32768
	ds_read_b128 v[208:211], v172 offset:33792
	ds_read_b128 v[212:215], v172 offset:34816
	ds_read_b128 v[216:219], v172 offset:35840
	ds_read_b128 v[220:223], v172 offset:36864
	ds_read_b128 v[224:227], v172 offset:37888
	ds_read_b128 v[228:231], v172 offset:38912
	ds_read_b128 v[232:235], v172 offset:39936
	global_load_lds_dwordx4 v138, s[38:39]
	s_mov_b32 m0, s43
	s_nop 0
	global_load_lds_dwordx4 v142, s[38:39]
	s_waitcnt vmcnt(8)
	s_waitcnt lgkmcnt(0)
	s_barrier
	v_mfma_f32_16x16x32_bf16 v[126:129], v[130:133], v[204:207], v[126:129]
	v_mfma_f32_16x16x32_bf16 v[122:125], v[178:181], v[204:207], v[122:125]
	v_mfma_f32_16x16x32_bf16 v[110:113], v[130:133], v[212:215], v[110:113]
	v_mfma_f32_16x16x32_bf16 v[106:109], v[178:181], v[212:215], v[106:109]
	v_mfma_f32_16x16x32_bf16 v[94:97], v[130:133], v[220:223], v[94:97]
	v_mfma_f32_16x16x32_bf16 v[90:93], v[178:181], v[220:223], v[90:93]
	v_mfma_f32_16x16x32_bf16 v[78:81], v[130:133], v[228:231], v[78:81]
	v_mfma_f32_16x16x32_bf16 v[74:77], v[178:181], v[228:231], v[74:77]
	v_mfma_f32_16x16x32_bf16 v[126:129], v[134:137], v[208:211], v[126:129]
	v_mfma_f32_16x16x32_bf16 v[122:125], v[182:185], v[208:211], v[122:125]
	v_mfma_f32_16x16x32_bf16 v[110:113], v[134:137], v[216:219], v[110:113]
	v_mfma_f32_16x16x32_bf16 v[106:109], v[182:185], v[216:219], v[106:109]
	v_mfma_f32_16x16x32_bf16 v[94:97], v[134:137], v[224:227], v[94:97]
	v_mfma_f32_16x16x32_bf16 v[90:93], v[182:185], v[224:227], v[90:93]
	v_mfma_f32_16x16x32_bf16 v[78:81], v[134:137], v[232:235], v[78:81]
	v_mfma_f32_16x16x32_bf16 v[74:77], v[182:185], v[232:235], v[74:77]
	v_mfma_f32_16x16x32_bf16 v[118:121], v[186:189], v[204:207], v[118:121]
	v_mfma_f32_16x16x32_bf16 v[114:117], v[194:197], v[204:207], v[114:117]
	v_mfma_f32_16x16x32_bf16 v[102:105], v[186:189], v[212:215], v[102:105]
	v_mfma_f32_16x16x32_bf16 v[98:101], v[194:197], v[212:215], v[98:101]
	v_mfma_f32_16x16x32_bf16 v[86:89], v[186:189], v[220:223], v[86:89]
	v_mfma_f32_16x16x32_bf16 v[82:85], v[194:197], v[220:223], v[82:85]
	v_mfma_f32_16x16x32_bf16 v[70:73], v[186:189], v[228:231], v[70:73]
	v_mfma_f32_16x16x32_bf16 v[66:69], v[194:197], v[228:231], v[66:69]
	v_mfma_f32_16x16x32_bf16 v[118:121], v[190:193], v[208:211], v[118:121]
	v_mfma_f32_16x16x32_bf16 v[114:117], v[200:203], v[208:211], v[114:117]
	v_mfma_f32_16x16x32_bf16 v[102:105], v[190:193], v[216:219], v[102:105]
	v_mfma_f32_16x16x32_bf16 v[98:101], v[200:203], v[216:219], v[98:101]
	v_mfma_f32_16x16x32_bf16 v[86:89], v[190:193], v[224:227], v[86:89]
	v_mfma_f32_16x16x32_bf16 v[82:85], v[200:203], v[224:227], v[82:85]
	v_mfma_f32_16x16x32_bf16 v[70:73], v[190:193], v[232:235], v[70:73]
	v_mfma_f32_16x16x32_bf16 v[66:69], v[200:203], v[232:235], v[66:69]
	s_barrier
	s_add_i32 s38, s57, s33
	s_add_u32 s36, s36, 0x80
	s_addc_u32 s37, s37, 0
	s_mov_b32 m0, s38
	ds_read_b128 v[204:207], v172 offset:49152
	ds_read_b128 v[208:211], v172 offset:50176
	ds_read_b128 v[212:215], v172 offset:51200
	ds_read_b128 v[216:219], v172 offset:52224
	ds_read_b128 v[220:223], v172 offset:53248
	ds_read_b128 v[224:227], v172 offset:54272
	ds_read_b128 v[228:231], v172 offset:55296
	ds_read_b128 v[232:235], v172 offset:56320
	global_load_lds_dwordx4 v140, s[36:37]
	s_add_i32 m0, s38, 0x2000
	s_add_i32 s38, s58, s33
	global_load_lds_dwordx4 v144, s[36:37]
	s_add_u32 s36, s36, 0x100000
	s_addc_u32 s37, s37, 0
	s_mov_b32 m0, s38
	s_nop 0
	global_load_lds_dwordx4 v140, s[36:37]
	s_add_i32 m0, s38, 0x2000
	s_nop 0
	global_load_lds_dwordx4 v144, s[36:37]
	s_waitcnt vmcnt(6)
	s_waitcnt lgkmcnt(0)
	s_barrier
	v_mfma_f32_16x16x32_bf16 v[62:65], v[130:133], v[204:207], v[62:65]
	v_mfma_f32_16x16x32_bf16 v[58:61], v[178:181], v[204:207], v[58:61]
	v_mfma_f32_16x16x32_bf16 v[46:49], v[130:133], v[212:215], v[46:49]
	v_mfma_f32_16x16x32_bf16 v[42:45], v[178:181], v[212:215], v[42:45]
	v_mfma_f32_16x16x32_bf16 v[30:33], v[130:133], v[220:223], v[30:33]
	v_mfma_f32_16x16x32_bf16 v[26:29], v[178:181], v[220:223], v[26:29]
	v_mfma_f32_16x16x32_bf16 v[14:17], v[130:133], v[228:231], v[14:17]
	v_mfma_f32_16x16x32_bf16 v[10:13], v[178:181], v[228:231], v[10:13]
	v_mfma_f32_16x16x32_bf16 v[62:65], v[134:137], v[208:211], v[62:65]
	v_mfma_f32_16x16x32_bf16 v[58:61], v[182:185], v[208:211], v[58:61]
	v_mfma_f32_16x16x32_bf16 v[46:49], v[134:137], v[216:219], v[46:49]
	v_mfma_f32_16x16x32_bf16 v[42:45], v[182:185], v[216:219], v[42:45]
	v_mfma_f32_16x16x32_bf16 v[30:33], v[134:137], v[224:227], v[30:33]
	v_mfma_f32_16x16x32_bf16 v[26:29], v[182:185], v[224:227], v[26:29]
	v_mfma_f32_16x16x32_bf16 v[14:17], v[134:137], v[232:235], v[14:17]
	v_mfma_f32_16x16x32_bf16 v[10:13], v[182:185], v[232:235], v[10:13]
	v_mfma_f32_16x16x32_bf16 v[54:57], v[186:189], v[204:207], v[54:57]
	v_mfma_f32_16x16x32_bf16 v[50:53], v[194:197], v[204:207], v[50:53]
	v_mfma_f32_16x16x32_bf16 v[38:41], v[186:189], v[212:215], v[38:41]
	v_mfma_f32_16x16x32_bf16 v[34:37], v[194:197], v[212:215], v[34:37]
	v_mfma_f32_16x16x32_bf16 v[22:25], v[186:189], v[220:223], v[22:25]
	v_mfma_f32_16x16x32_bf16 v[18:21], v[194:197], v[220:223], v[18:21]
	v_mfma_f32_16x16x32_bf16 v[6:9], v[186:189], v[228:231], v[6:9]
	v_mfma_f32_16x16x32_bf16 v[2:5], v[194:197], v[228:231], v[2:5]
	v_mfma_f32_16x16x32_bf16 v[54:57], v[190:193], v[208:211], v[54:57]
	v_mfma_f32_16x16x32_bf16 v[50:53], v[200:203], v[208:211], v[50:53]
	v_mfma_f32_16x16x32_bf16 v[38:41], v[190:193], v[216:219], v[38:41]
	v_mfma_f32_16x16x32_bf16 v[34:37], v[200:203], v[216:219], v[34:37]
	v_mfma_f32_16x16x32_bf16 v[22:25], v[190:193], v[224:227], v[22:25]
	v_mfma_f32_16x16x32_bf16 v[18:21], v[200:203], v[224:227], v[18:21]
	v_mfma_f32_16x16x32_bf16 v[6:9], v[190:193], v[232:235], v[6:9]
	v_mfma_f32_16x16x32_bf16 v[2:5], v[200:203], v[232:235], v[2:5]
	s_barrier
	s_add_i32 s56, s56, 2
	s_add_u32 s34, s34, 0x100
	s_addc_u32 s35, s35, 0
	s_add_u32 s54, s54, 0x100
	s_addc_u32 s55, s55, 0
	s_cmp_gt_u32 s56, 61
	s_cbranch_scc0 .LBB0_180
	s_and_b64 vcc, exec, s[12:13]
	s_cbranch_vccz .LBB0_183
	s_barrier

; #define PG8_STAGE(bufoff, gbase, voff) do { _Pragma("unroll") for (int _i = 0; _i < 2; ++_i) \
;         __builtin_amdgcn_global_load_lds((const unsigned*)((const char*)(gbase) + (voff)[_i]), (PG8_LAS unsigned*)(lds + (bufoff) + ldsw + _i * 8192), 16, 0, 0); } while (0)
; #define PG8_LDA(dst, b, h) do { _Pragma("unroll") for (int m = 0; m < 4; ++m) _Pragma("unroll") for (int k = 0; k < 2; ++k) dst[m][k] = *(const PG8_LAS bf16x8*)(lds + PG8_SA(b, h) + aoff + m * 2048 + k * 1024); } while (0)
; #define PG8_LDB(dst, b, h) do { _Pragma("unroll") for (int n = 0; n < 2; ++n) _Pragma("unroll") for (int k = 0; k < 2; ++k) dst[n][k] = *(const PG8_LAS bf16x8*)(lds + PG8_SB(b, h) + boff + n * 2048 + k * 1024); } while (0)
; #define PG8_MMA(ai, bj, At, Bt) do { __builtin_amdgcn_s_setprio(1); _Pragma("unroll") for (int m = 0; m < 4; ++m) _Pragma("unroll") for (int n = 0; n < 2; ++n) _Pragma("unroll") for (int k = 0; k < 2; ++k) \
;         acc[ai][bj][m][n] = __builtin_amdgcn_mfma_f32_16x16x32_bf16(Bt[n][k], At[m][k], acc[ai][bj][m][n], 0, 0, 0); __builtin_amdgcn_s_setprio(0); } while (0)
; #define PG8_WAIT_V(n) asm volatile("s_waitcnt vmcnt(" #n ")" ::: "memory")
; #define PG8_WAIT_L(n) asm volatile("s_waitcnt lgkmcnt(" #n ")" ::: "memory")
; #define PG8_BAR __builtin_amdgcn_s_barrier()
; #define PG8_SCHED __builtin_amdgcn_sched_barrier(0)
; template <class Epi, class Sched, bool ALIGN_EPI = false, bool SP2 = false>
; __device__ __forceinline__ void gemm_phase(PG8_LAS unsigned char* lds, const Gemm g, const Sched& S, const Epi& E) {
;     ...
;             PG8_LDB(B0, 0, 0); PG8_LDB(B1, 0, 1); PG8_SCHED; PG8_LDA(At, 0, 0); PG8_STAGE(PG8_SA(1, 1), a1 + hstep, voffA);
;             PG8_WAIT_V(8); PG8_WAIT_L(0); PG8_BAR; PG8_MMA(0, 0, At, B0); PG8_MMA(0, 1, At, B1); PG8_BAR; PG8_SCHED;
;             PG8_LDA(At, 0, 1); PG8_STAGE(PG8_SB(0, 0), b2, voffB); PG8_STAGE(PG8_SB(0, 1), b2 + hstep, voffB); PG8_STAGE(PG8_SA(0, 0), a2, voffA);
;             PG8_WAIT_V(8); PG8_WAIT_L(0); PG8_BAR; PG8_MMA(1, 0, At, B0); PG8_MMA(1, 1, At, B1); PG8_BAR; PG8_SCHED;
.LBB0_857:
	s_add_u32 s34, s30, 0xfff80000
	s_addc_u32 s35, s31, -1
	s_mov_b32 m0, s43
	s_nop 0
	global_load_lds_dwordx4 v150, s[34:35]
	s_mov_b32 m0, s44
	s_nop 0
	global_load_lds_dwordx4 v154, s[34:35]
	s_add_u32 s34, s34, 0x80
	s_addc_u32 s35, s35, 0
	ds_read_b128 v[130:133], v180
	ds_read_b128 v[134:137], v180 offset:1024
	ds_read_b128 v[138:141], v180 offset:2048
	ds_read_b128 v[142:145], v180 offset:3072
	ds_read_b128 v[146:149], v181
	ds_read_b128 v[166:169], v181 offset:1024
	ds_read_b128 v[170:173], v181 offset:2048
	ds_read_b128 v[174:177], v181 offset:3072
	s_cmp_eq_u32 s56, 28
	s_cselect_b32 s37, s15, s35
	s_cselect_b32 s36, s50, s34
	s_cselect_b32 s35, s13, s53
	s_cselect_b32 s34, s51, s52
	s_add_i32 m0, s29, 0xc000
	ds_read_b128 v[184:187], v182
	ds_read_b128 v[188:191], v182 offset:1024
	ds_read_b128 v[192:195], v182 offset:2048
	ds_read_b128 v[200:203], v182 offset:3072
	ds_read_b128 v[204:207], v182 offset:4096
	ds_read_b128 v[208:211], v182 offset:5120
	ds_read_b128 v[212:215], v182 offset:6144
	ds_read_b128 v[216:219], v182 offset:7168
	global_load_lds_dwordx4 v158, s[30:31]
	s_add_i32 m0, s29, 0xe000
	s_nop 0
	global_load_lds_dwordx4 v160, s[30:31]
	s_waitcnt vmcnt(8)
	s_waitcnt lgkmcnt(0)
	s_barrier
	v_mfma_f32_16x16x32_bf16 v[126:129], v[130:133], v[184:187], v[126:129]
	v_mfma_f32_16x16x32_bf16 v[122:125], v[138:141], v[184:187], v[122:125]
	v_mfma_f32_16x16x32_bf16 v[110:113], v[130:133], v[192:195], v[110:113]
	v_mfma_f32_16x16x32_bf16 v[106:109], v[138:141], v[192:195], v[106:109]
	v_mfma_f32_16x16x32_bf16 v[94:97], v[130:133], v[204:207], v[94:97]
	v_mfma_f32_16x16x32_bf16 v[90:93], v[138:141], v[204:207], v[90:93]
	v_mfma_f32_16x16x32_bf16 v[78:81], v[130:133], v[212:215], v[78:81]
	v_mfma_f32_16x16x32_bf16 v[74:77], v[138:141], v[212:215], v[74:77]
	v_mfma_f32_16x16x32_bf16 v[126:129], v[134:137], v[188:191], v[126:129]
	v_mfma_f32_16x16x32_bf16 v[122:125], v[142:145], v[188:191], v[122:125]
	v_mfma_f32_16x16x32_bf16 v[110:113], v[134:137], v[200:203], v[110:113]
	v_mfma_f32_16x16x32_bf16 v[106:109], v[142:145], v[200:203], v[106:109]
	v_mfma_f32_16x16x32_bf16 v[94:97], v[134:137], v[208:211], v[94:97]
	v_mfma_f32_16x16x32_bf16 v[90:93], v[142:145], v[208:211], v[90:93]
	v_mfma_f32_16x16x32_bf16 v[78:81], v[134:137], v[216:219], v[78:81]
	v_mfma_f32_16x16x32_bf16 v[74:77], v[142:145], v[216:219], v[74:77]
	v_mfma_f32_16x16x32_bf16 v[118:121], v[146:149], v[184:187], v[118:121]
	v_mfma_f32_16x16x32_bf16 v[114:117], v[170:173], v[184:187], v[114:117]
	v_mfma_f32_16x16x32_bf16 v[102:105], v[146:149], v[192:195], v[102:105]
	v_mfma_f32_16x16x32_bf16 v[98:101], v[170:173], v[192:195], v[98:101]
	v_mfma_f32_16x16x32_bf16 v[86:89], v[146:149], v[204:207], v[86:89]
	v_mfma_f32_16x16x32_bf16 v[82:85], v[170:173], v[204:207], v[82:85]
	v_mfma_f32_16x16x32_bf16 v[70:73], v[146:149], v[212:215], v[70:73]
	v_mfma_f32_16x16x32_bf16 v[66:69], v[170:173], v[212:215], v[66:69]
	v_mfma_f32_16x16x32_bf16 v[118:121], v[166:169], v[188:191], v[118:121]
	v_mfma_f32_16x16x32_bf16 v[114:117], v[174:177], v[188:191], v[114:117]
	v_mfma_f32_16x16x32_bf16 v[102:105], v[166:169], v[200:203], v[102:105]
	v_mfma_f32_16x16x32_bf16 v[98:101], v[174:177], v[200:203], v[98:101]
	v_mfma_f32_16x16x32_bf16 v[86:89], v[166:169], v[208:211], v[86:89]
	v_mfma_f32_16x16x32_bf16 v[82:85], v[174:177], v[208:211], v[82:85]
	v_mfma_f32_16x16x32_bf16 v[70:73], v[166:169], v[216:219], v[70:73]
	v_mfma_f32_16x16x32_bf16 v[66:69], v[174:177], v[216:219], v[66:69]
	s_barrier
	s_add_i32 s57, s46, s38
	s_mov_b32 m0, s57
	ds_read_b128 v[184:187], v182 offset:16384
	ds_read_b128 v[188:191], v182 offset:17408
	ds_read_b128 v[192:195], v182 offset:18432
	ds_read_b128 v[200:203], v182 offset:19456
	ds_read_b128 v[204:207], v182 offset:20480
	ds_read_b128 v[208:211], v182 offset:21504
	ds_read_b128 v[212:215], v182 offset:22528
	ds_read_b128 v[216:219], v182 offset:23552
	global_load_lds_dwordx4 v152, s[34:35]
	s_add_i32 m0, s57, 0x2000
	s_add_u32 s58, s34, 0x80000
	s_addc_u32 s59, s35, 0
	s_add_i32 s57, s47, s38
	global_load_lds_dwordx4 v156, s[34:35]
	s_mov_b32 m0, s57
	s_nop 0
	global_load_lds_dwordx4 v152, s[58:59]
	s_add_i32 m0, s57, 0x2000
	s_nop 0
	global_load_lds_dwordx4 v156, s[58:59]
	s_waitcnt vmcnt(6)
	s_waitcnt lgkmcnt(0)
	s_barrier
	v_mfma_f32_16x16x32_bf16 v[62:65], v[130:133], v[184:187], v[62:65]
	v_mfma_f32_16x16x32_bf16 v[58:61], v[138:141], v[184:187], v[58:61]
	v_mfma_f32_16x16x32_bf16 v[46:49], v[130:133], v[192:195], v[46:49]
	v_mfma_f32_16x16x32_bf16 v[42:45], v[138:141], v[192:195], v[42:45]
	v_mfma_f32_16x16x32_bf16 v[30:33], v[130:133], v[204:207], v[30:33]
	v_mfma_f32_16x16x32_bf16 v[26:29], v[138:141], v[204:207], v[26:29]
	v_mfma_f32_16x16x32_bf16 v[14:17], v[130:133], v[212:215], v[14:17]
	v_mfma_f32_16x16x32_bf16 v[10:13], v[138:141], v[212:215], v[10:13]
	v_mfma_f32_16x16x32_bf16 v[62:65], v[134:137], v[188:191], v[62:65]
	v_mfma_f32_16x16x32_bf16 v[58:61], v[142:145], v[188:191], v[58:61]
	v_mfma_f32_16x16x32_bf16 v[46:49], v[134:137], v[200:203], v[46:49]
	v_mfma_f32_16x16x32_bf16 v[42:45], v[142:145], v[200:203], v[42:45]
	v_mfma_f32_16x16x32_bf16 v[30:33], v[134:137], v[208:211], v[30:33]
	v_mfma_f32_16x16x32_bf16 v[26:29], v[142:145], v[208:211], v[26:29]
	v_mfma_f32_16x16x32_bf16 v[14:17], v[134:137], v[216:219], v[14:17]
	v_mfma_f32_16x16x32_bf16 v[10:13], v[142:145], v[216:219], v[10:13]
	v_mfma_f32_16x16x32_bf16 v[54:57], v[146:149], v[184:187], v[54:57]
	v_mfma_f32_16x16x32_bf16 v[50:53], v[170:173], v[184:187], v[50:53]
	v_mfma_f32_16x16x32_bf16 v[38:41], v[146:149], v[192:195], v[38:41]
	v_mfma_f32_16x16x32_bf16 v[34:37], v[170:173], v[192:195], v[34:37]
	v_mfma_f32_16x16x32_bf16 v[22:25], v[146:149], v[204:207], v[22:25]
	v_mfma_f32_16x16x32_bf16 v[18:21], v[170:173], v[204:207], v[18:21]
	v_mfma_f32_16x16x32_bf16 v[6:9], v[146:149], v[212:215], v[6:9]
	v_mfma_f32_16x16x32_bf16 v[2:5], v[170:173], v[212:215], v[2:5]
	v_mfma_f32_16x16x32_bf16 v[54:57], v[166:169], v[188:191], v[54:57]
	v_mfma_f32_16x16x32_bf16 v[50:53], v[174:177], v[188:191], v[50:53]
	v_mfma_f32_16x16x32_bf16 v[38:41], v[166:169], v[200:203], v[38:41]
	v_mfma_f32_16x16x32_bf16 v[34:37], v[174:177], v[200:203], v[34:37]
	v_mfma_f32_16x16x32_bf16 v[22:25], v[166:169], v[208:211], v[22:25]
	v_mfma_f32_16x16x32_bf16 v[18:21], v[174:177], v[208:211], v[18:21]
	v_mfma_f32_16x16x32_bf16 v[6:9], v[166:169], v[216:219], v[6:9]
	v_mfma_f32_16x16x32_bf16 v[2:5], v[174:177], v[216:219], v[2:5]
	s_barrier
; #define PG8_STAGE(bufoff, gbase, voff) do { _Pragma("unroll") for (int _i = 0; _i < 2; ++_i) \
;         __builtin_amdgcn_global_load_lds((const unsigned*)((const char*)(gbase) + (voff)[_i]), (PG8_LAS unsigned*)(lds + (bufoff) + ldsw + _i * 8192), 16, 0, 0); } while (0)
; #define PG8_LDA(dst, b, h) do { _Pragma("unroll") for (int m = 0; m < 4; ++m) _Pragma("unroll") for (int k = 0; k < 2; ++k) dst[m][k] = *(const PG8_LAS bf16x8*)(lds + PG8_SA(b, h) + aoff + m * 2048 + k * 1024); } while (0)
; #define PG8_LDB(dst, b, h) do { _Pragma("unroll") for (int n = 0; n < 2; ++n) _Pragma("unroll") for (int k = 0; k < 2; ++k) dst[n][k] = *(const PG8_LAS bf16x8*)(lds + PG8_SB(b, h) + boff + n * 2048 + k * 1024); } while (0)
; #define PG8_MMA(ai, bj, At, Bt) do { __builtin_amdgcn_s_setprio(1); _Pragma("unroll") for (int m = 0; m < 4; ++m) _Pragma("unroll") for (int n = 0; n < 2; ++n) _Pragma("unroll") for (int k = 0; k < 2; ++k) \
;         acc[ai][bj][m][n] = __builtin_amdgcn_mfma_f32_16x16x32_bf16(Bt[n][k], At[m][k], acc[ai][bj][m][n], 0, 0, 0); __builtin_amdgcn_s_setprio(0); } while (0)
; #define PG8_WAIT_V(n) asm volatile("s_waitcnt vmcnt(" #n ")" ::: "memory")
; #define PG8_WAIT_L(n) asm volatile("s_waitcnt lgkmcnt(" #n ")" ::: "memory")
; #define PG8_BAR __builtin_amdgcn_s_barrier()
; #define PG8_SCHED __builtin_amdgcn_sched_barrier(0)
; template <class Epi, class Sched, bool ALIGN_EPI = false, bool SP2 = false>
; __device__ __forceinline__ void gemm_phase(PG8_LAS unsigned char* lds, const Gemm g, const Sched& S, const Epi& E) {
;     ...
;         for (int t = 0; t < nt; t += 2) {
;             const bool last = (t == nt - 2);
;             const char* a1 = cA + (size_t)(t + 1) * kstep;
;             const char* a2 = last ? nA : cA + (size_t)(t + 2) * kstep; const char* b2 = last ? nB : cB + (size_t)(t + 2) * kstep;
;     ...
;             PG8_LDB(B0, 1, 0); PG8_LDB(B1, 1, 1); PG8_SCHED; PG8_LDA(At, 1, 0); PG8_STAGE(PG8_SA(0, 1), a2 + hstep, voffA);
;             PG8_WAIT_V(8); PG8_WAIT_L(0); PG8_BAR; PG8_MMA(0, 0, At, B0); PG8_MMA(0, 1, At, B1); PG8_BAR; PG8_SCHED;
;             PG8_LDA(At, 1, 1); PG8_STAGE(PG8_SB(1, 0), b3, voffB); PG8_STAGE(PG8_SB(1, 1), b3 + hstep, voffB); PG8_STAGE(PG8_SA(1, 0), a3, voffA);
;             PG8_WAIT_V(8); PG8_WAIT_L(0); PG8_BAR; PG8_MMA(1, 0, At, B0); PG8_MMA(1, 1, At, B1); PG8_BAR; PG8_SCHED;
	s_mov_b32 m0, s29
	s_nop 0
	global_load_lds_dwordx4 v150, s[36:37]
	s_mov_b32 m0, s39
	s_nop 0
	global_load_lds_dwordx4 v154, s[36:37]
	s_add_i32 s57, 0, 0x18000
	s_add_i32 s58, 0, 0x1c000
	v_add_u32_e32 v142, s57, v178
	v_add_u32_e32 v174, s58, v178
	ds_read_b128 v[130:133], v142
	ds_read_b128 v[134:137], v142 offset:1024
	ds_read_b128 v[138:141], v142 offset:2048
	ds_read_b128 v[142:145], v142 offset:3072
	ds_read_b128 v[146:149], v174
	ds_read_b128 v[166:169], v174 offset:1024
	ds_read_b128 v[170:173], v174 offset:2048
	ds_read_b128 v[174:177], v174 offset:3072
	s_add_u32 s36, s36, 0x80000
	s_addc_u32 s37, s37, 0
	s_mov_b32 m0, s40
	ds_read_b128 v[184:187], v182 offset:32768
	ds_read_b128 v[188:191], v182 offset:33792
	ds_read_b128 v[192:195], v182 offset:34816
	ds_read_b128 v[200:203], v182 offset:35840
	ds_read_b128 v[204:207], v182 offset:36864
	ds_read_b128 v[208:211], v182 offset:37888
	ds_read_b128 v[212:215], v182 offset:38912
	ds_read_b128 v[216:219], v182 offset:39936
	global_load_lds_dwordx4 v150, s[36:37]
	s_mov_b32 m0, s41
	s_nop 0
	global_load_lds_dwordx4 v154, s[36:37]
	s_waitcnt vmcnt(8)
	s_waitcnt lgkmcnt(0)
	s_barrier
	v_mfma_f32_16x16x32_bf16 v[126:129], v[130:133], v[184:187], v[126:129]
	v_mfma_f32_16x16x32_bf16 v[122:125], v[138:141], v[184:187], v[122:125]
	v_mfma_f32_16x16x32_bf16 v[110:113], v[130:133], v[192:195], v[110:113]
	v_mfma_f32_16x16x32_bf16 v[106:109], v[138:141], v[192:195], v[106:109]
	v_mfma_f32_16x16x32_bf16 v[94:97], v[130:133], v[204:207], v[94:97]
	v_mfma_f32_16x16x32_bf16 v[90:93], v[138:141], v[204:207], v[90:93]
	v_mfma_f32_16x16x32_bf16 v[78:81], v[130:133], v[212:215], v[78:81]
	v_mfma_f32_16x16x32_bf16 v[74:77], v[138:141], v[212:215], v[74:77]
	v_mfma_f32_16x16x32_bf16 v[126:129], v[134:137], v[188:191], v[126:129]
	v_mfma_f32_16x16x32_bf16 v[122:125], v[142:145], v[188:191], v[122:125]
	v_mfma_f32_16x16x32_bf16 v[110:113], v[134:137], v[200:203], v[110:113]
	v_mfma_f32_16x16x32_bf16 v[106:109], v[142:145], v[200:203], v[106:109]
	v_mfma_f32_16x16x32_bf16 v[94:97], v[134:137], v[208:211], v[94:97]
	v_mfma_f32_16x16x32_bf16 v[90:93], v[142:145], v[208:211], v[90:93]
	v_mfma_f32_16x16x32_bf16 v[78:81], v[134:137], v[216:219], v[78:81]
	v_mfma_f32_16x16x32_bf16 v[74:77], v[142:145], v[216:219], v[74:77]
	v_mfma_f32_16x16x32_bf16 v[118:121], v[146:149], v[184:187], v[118:121]
	v_mfma_f32_16x16x32_bf16 v[114:117], v[170:173], v[184:187], v[114:117]
	v_mfma_f32_16x16x32_bf16 v[102:105], v[146:149], v[192:195], v[102:105]
	v_mfma_f32_16x16x32_bf16 v[98:101], v[170:173], v[192:195], v[98:101]
	v_mfma_f32_16x16x32_bf16 v[86:89], v[146:149], v[204:207], v[86:89]
	v_mfma_f32_16x16x32_bf16 v[82:85], v[170:173], v[204:207], v[82:85]
	v_mfma_f32_16x16x32_bf16 v[70:73], v[146:149], v[212:215], v[70:73]
	v_mfma_f32_16x16x32_bf16 v[66:69], v[170:173], v[212:215], v[66:69]
	v_mfma_f32_16x16x32_bf16 v[118:121], v[166:169], v[188:191], v[118:121]
	v_mfma_f32_16x16x32_bf16 v[114:117], v[174:177], v[188:191], v[114:117]
	v_mfma_f32_16x16x32_bf16 v[102:105], v[166:169], v[200:203], v[102:105]
	v_mfma_f32_16x16x32_bf16 v[98:101], v[174:177], v[200:203], v[98:101]
	v_mfma_f32_16x16x32_bf16 v[86:89], v[166:169], v[208:211], v[86:89]
	v_mfma_f32_16x16x32_bf16 v[82:85], v[174:177], v[208:211], v[82:85]
	v_mfma_f32_16x16x32_bf16 v[70:73], v[166:169], v[216:219], v[70:73]
	v_mfma_f32_16x16x32_bf16 v[66:69], v[174:177], v[216:219], v[66:69]
	s_barrier
	s_add_i32 s36, s57, s38
	s_add_u32 s34, s34, 0x80
	s_addc_u32 s35, s35, 0
	s_mov_b32 m0, s36
	ds_read_b128 v[184:187], v182 offset:49152
	ds_read_b128 v[188:191], v182 offset:50176
	ds_read_b128 v[192:195], v182 offset:51200
	ds_read_b128 v[200:203], v182 offset:52224
	ds_read_b128 v[204:207], v182 offset:53248
	ds_read_b128 v[208:211], v182 offset:54272
	ds_read_b128 v[212:215], v182 offset:55296
	ds_read_b128 v[216:219], v182 offset:56320
	global_load_lds_dwordx4 v152, s[34:35]
	s_add_i32 m0, s36, 0x2000
	s_add_i32 s36, s58, s38
	global_load_lds_dwordx4 v156, s[34:35]
	s_add_u32 s34, s34, 0x80000
	s_addc_u32 s35, s35, 0
	s_mov_b32 m0, s36
	s_nop 0
	global_load_lds_dwordx4 v152, s[34:35]
	s_add_i32 m0, s36, 0x2000
	s_nop 0
	global_load_lds_dwordx4 v156, s[34:35]
	s_waitcnt vmcnt(6)
	s_waitcnt lgkmcnt(0)
	s_barrier
	v_mfma_f32_16x16x32_bf16 v[62:65], v[130:133], v[184:187], v[62:65]
	v_mfma_f32_16x16x32_bf16 v[58:61], v[138:141], v[184:187], v[58:61]
	v_mfma_f32_16x16x32_bf16 v[46:49], v[130:133], v[192:195], v[46:49]
	v_mfma_f32_16x16x32_bf16 v[42:45], v[138:141], v[192:195], v[42:45]
	v_mfma_f32_16x16x32_bf16 v[30:33], v[130:133], v[204:207], v[30:33]
	v_mfma_f32_16x16x32_bf16 v[26:29], v[138:141], v[204:207], v[26:29]
	v_mfma_f32_16x16x32_bf16 v[14:17], v[130:133], v[212:215], v[14:17]
	v_mfma_f32_16x16x32_bf16 v[10:13], v[138:141], v[212:215], v[10:13]
	v_mfma_f32_16x16x32_bf16 v[62:65], v[134:137], v[188:191], v[62:65]
	v_mfma_f32_16x16x32_bf16 v[58:61], v[142:145], v[188:191], v[58:61]
	v_mfma_f32_16x16x32_bf16 v[46:49], v[134:137], v[200:203], v[46:49]
	v_mfma_f32_16x16x32_bf16 v[42:45], v[142:145], v[200:203], v[42:45]
	v_mfma_f32_16x16x32_bf16 v[30:33], v[134:137], v[208:211], v[30:33]
	v_mfma_f32_16x16x32_bf16 v[26:29], v[142:145], v[208:211], v[26:29]
	v_mfma_f32_16x16x32_bf16 v[14:17], v[134:137], v[216:219], v[14:17]
	v_mfma_f32_16x16x32_bf16 v[10:13], v[142:145], v[216:219], v[10:13]
	v_mfma_f32_16x16x32_bf16 v[54:57], v[146:149], v[184:187], v[54:57]
	v_mfma_f32_16x16x32_bf16 v[50:53], v[170:173], v[184:187], v[50:53]
	v_mfma_f32_16x16x32_bf16 v[38:41], v[146:149], v[192:195], v[38:41]
	v_mfma_f32_16x16x32_bf16 v[34:37], v[170:173], v[192:195], v[34:37]
	v_mfma_f32_16x16x32_bf16 v[22:25], v[146:149], v[204:207], v[22:25]
	v_mfma_f32_16x16x32_bf16 v[18:21], v[170:173], v[204:207], v[18:21]
	v_mfma_f32_16x16x32_bf16 v[6:9], v[146:149], v[212:215], v[6:9]
	v_mfma_f32_16x16x32_bf16 v[2:5], v[170:173], v[212:215], v[2:5]
	v_mfma_f32_16x16x32_bf16 v[54:57], v[166:169], v[188:191], v[54:57]
	v_mfma_f32_16x16x32_bf16 v[50:53], v[174:177], v[188:191], v[50:53]
	v_mfma_f32_16x16x32_bf16 v[38:41], v[166:169], v[200:203], v[38:41]
	v_mfma_f32_16x16x32_bf16 v[34:37], v[174:177], v[200:203], v[34:37]
	v_mfma_f32_16x16x32_bf16 v[22:25], v[166:169], v[208:211], v[22:25]
	v_mfma_f32_16x16x32_bf16 v[18:21], v[174:177], v[208:211], v[18:21]
	v_mfma_f32_16x16x32_bf16 v[6:9], v[166:169], v[216:219], v[6:9]
	v_mfma_f32_16x16x32_bf16 v[2:5], v[174:177], v[216:219], v[2:5]
	s_barrier
	s_add_i32 s56, s56, 2
	s_add_u32 s30, s30, 0x100
	s_addc_u32 s31, s31, 0
	s_add_u32 s52, s52, 0x100
	s_addc_u32 s53, s53, 0
	s_cmp_gt_u32 s56, 29
	s_cbranch_scc0 .LBB0_857
	s_and_b64 vcc, exec, s[10:11]
	s_cbranch_vccz .LBB0_860
	s_barrier

; #define PG8_STAGE(bufoff, gbase, voff) do { _Pragma("unroll") for (int _i = 0; _i < 2; ++_i) \
;         __builtin_amdgcn_global_load_lds((const unsigned*)((const char*)(gbase) + (voff)[_i]), (PG8_LAS unsigned*)(lds + (bufoff) + ldsw + _i * 8192), 16, 0, 0); } while (0)
; #define PG8_LDA(dst, b, h) do { _Pragma("unroll") for (int m = 0; m < 4; ++m) _Pragma("unroll") for (int k = 0; k < 2; ++k) dst[m][k] = *(const PG8_LAS bf16x8*)(lds + PG8_SA(b, h) + aoff + m * 2048 + k * 1024); } while (0)
; #define PG8_LDB(dst, b, h) do { _Pragma("unroll") for (int n = 0; n < 2; ++n) _Pragma("unroll") for (int k = 0; k < 2; ++k) dst[n][k] = *(const PG8_LAS bf16x8*)(lds + PG8_SB(b, h) + boff + n * 2048 + k * 1024); } while (0)
; #define PG8_MMA(ai, bj, At, Bt) do { __builtin_amdgcn_s_setprio(1); _Pragma("unroll") for (int m = 0; m < 4; ++m) _Pragma("unroll") for (int n = 0; n < 2; ++n) _Pragma("unroll") for (int k = 0; k < 2; ++k) \
;         acc[ai][bj][m][n] = __builtin_amdgcn_mfma_f32_16x16x32_bf16(Bt[n][k], At[m][k], acc[ai][bj][m][n], 0, 0, 0); __builtin_amdgcn_s_setprio(0); } while (0)
; #define PG8_WAIT_V(n) asm volatile("s_waitcnt vmcnt(" #n ")" ::: "memory")
; #define PG8_WAIT_L(n) asm volatile("s_waitcnt lgkmcnt(" #n ")" ::: "memory")
; #define PG8_BAR __builtin_amdgcn_s_barrier()
; #define PG8_SCHED __builtin_amdgcn_sched_barrier(0)
; template <class Epi, class Sched, bool ALIGN_EPI = false, bool SP2 = false>
; __device__ __forceinline__ void gemm_phase(PG8_LAS unsigned char* lds, const Gemm g, const Sched& S, const Epi& E) {
;     ...
;             PG8_LDB(B0, 0, 0); PG8_LDB(B1, 0, 1); PG8_SCHED; PG8_LDA(At, 0, 0); PG8_STAGE(PG8_SA(1, 1), a1 + hstep, voffA);
;             PG8_WAIT_V(8); PG8_WAIT_L(0); PG8_BAR; PG8_MMA(0, 0, At, B0); PG8_MMA(0, 1, At, B1); PG8_BAR; PG8_SCHED;
;             PG8_LDA(At, 0, 1); PG8_STAGE(PG8_SB(0, 0), b2, voffB); PG8_STAGE(PG8_SB(0, 1), b2 + hstep, voffB); PG8_STAGE(PG8_SA(0, 0), a2, voffA);
;             PG8_WAIT_V(8); PG8_WAIT_L(0); PG8_BAR; PG8_MMA(1, 0, At, B0); PG8_MMA(1, 1, At, B1); PG8_BAR; PG8_SCHED;
.LBB0_884:
	s_add_u32 s34, s30, 0xfff80000
	s_addc_u32 s35, s31, -1
	s_mov_b32 m0, s43
	s_nop 0
	global_load_lds_dwordx4 v178, s[34:35]
	s_mov_b32 m0, s44
	s_nop 0
	global_load_lds_dwordx4 v182, s[34:35]
	s_add_u32 s34, s34, 0x80
	s_addc_u32 s35, s35, 0
	ds_read_b128 v[130:133], v211
	ds_read_b128 v[134:137], v211 offset:1024
	ds_read_b128 v[138:141], v211 offset:2048
	ds_read_b128 v[142:145], v211 offset:3072
	ds_read_b128 v[146:149], v212
	ds_read_b128 v[150:153], v212 offset:1024
	ds_read_b128 v[154:157], v212 offset:2048
	ds_read_b128 v[158:161], v212 offset:3072
	s_cmp_eq_u32 s56, 28
	s_cselect_b32 s37, s15, s35
	s_cselect_b32 s36, s50, s34
	s_cselect_b32 s35, s13, s53
	s_cselect_b32 s34, s51, s52
	s_add_i32 m0, s29, 0xc000
	ds_read_b128 v[162:165], v213
	ds_read_b128 v[166:169], v213 offset:1024
	ds_read_b128 v[170:173], v213 offset:2048
	ds_read_b128 v[174:177], v213 offset:3072
	ds_read_b128 v[194:197], v213 offset:4096
	ds_read_b128 v[200:203], v213 offset:5120
	ds_read_b128 v[204:207], v213 offset:6144
	ds_read_b128 v[214:217], v213 offset:7168
	global_load_lds_dwordx4 v186, s[30:31]
	s_add_i32 m0, s29, 0xe000
	s_nop 0
	global_load_lds_dwordx4 v188, s[30:31]
	s_waitcnt vmcnt(8)
	s_waitcnt lgkmcnt(0)
	s_barrier
	v_mfma_f32_16x16x32_bf16 v[126:129], v[130:133], v[162:165], v[126:129]
	v_mfma_f32_16x16x32_bf16 v[122:125], v[138:141], v[162:165], v[122:125]
	v_mfma_f32_16x16x32_bf16 v[110:113], v[130:133], v[170:173], v[110:113]
	v_mfma_f32_16x16x32_bf16 v[106:109], v[138:141], v[170:173], v[106:109]
	v_mfma_f32_16x16x32_bf16 v[94:97], v[130:133], v[194:197], v[94:97]
	v_mfma_f32_16x16x32_bf16 v[90:93], v[138:141], v[194:197], v[90:93]
	v_mfma_f32_16x16x32_bf16 v[78:81], v[130:133], v[204:207], v[78:81]
	v_mfma_f32_16x16x32_bf16 v[74:77], v[138:141], v[204:207], v[74:77]
	v_mfma_f32_16x16x32_bf16 v[126:129], v[134:137], v[166:169], v[126:129]
	v_mfma_f32_16x16x32_bf16 v[122:125], v[142:145], v[166:169], v[122:125]
	v_mfma_f32_16x16x32_bf16 v[110:113], v[134:137], v[174:177], v[110:113]
	v_mfma_f32_16x16x32_bf16 v[106:109], v[142:145], v[174:177], v[106:109]
	v_mfma_f32_16x16x32_bf16 v[94:97], v[134:137], v[200:203], v[94:97]
	v_mfma_f32_16x16x32_bf16 v[90:93], v[142:145], v[200:203], v[90:93]
	v_mfma_f32_16x16x32_bf16 v[78:81], v[134:137], v[214:217], v[78:81]
	v_mfma_f32_16x16x32_bf16 v[74:77], v[142:145], v[214:217], v[74:77]
	v_mfma_f32_16x16x32_bf16 v[118:121], v[146:149], v[162:165], v[118:121]
	v_mfma_f32_16x16x32_bf16 v[114:117], v[154:157], v[162:165], v[114:117]
	v_mfma_f32_16x16x32_bf16 v[102:105], v[146:149], v[170:173], v[102:105]
	v_mfma_f32_16x16x32_bf16 v[98:101], v[154:157], v[170:173], v[98:101]
	v_mfma_f32_16x16x32_bf16 v[86:89], v[146:149], v[194:197], v[86:89]
	v_mfma_f32_16x16x32_bf16 v[82:85], v[154:157], v[194:197], v[82:85]
	v_mfma_f32_16x16x32_bf16 v[70:73], v[146:149], v[204:207], v[70:73]
	v_mfma_f32_16x16x32_bf16 v[66:69], v[154:157], v[204:207], v[66:69]
	v_mfma_f32_16x16x32_bf16 v[118:121], v[150:153], v[166:169], v[118:121]
	v_mfma_f32_16x16x32_bf16 v[114:117], v[158:161], v[166:169], v[114:117]
	v_mfma_f32_16x16x32_bf16 v[102:105], v[150:153], v[174:177], v[102:105]
	v_mfma_f32_16x16x32_bf16 v[98:101], v[158:161], v[174:177], v[98:101]
	v_mfma_f32_16x16x32_bf16 v[86:89], v[150:153], v[200:203], v[86:89]
	v_mfma_f32_16x16x32_bf16 v[82:85], v[158:161], v[200:203], v[82:85]
	v_mfma_f32_16x16x32_bf16 v[70:73], v[150:153], v[214:217], v[70:73]
	v_mfma_f32_16x16x32_bf16 v[66:69], v[158:161], v[214:217], v[66:69]
	s_barrier
	s_add_i32 s57, s46, s38
	s_mov_b32 m0, s57
	ds_read_b128 v[162:165], v213 offset:16384
	ds_read_b128 v[166:169], v213 offset:17408
	ds_read_b128 v[170:173], v213 offset:18432
	ds_read_b128 v[174:177], v213 offset:19456
	ds_read_b128 v[194:197], v213 offset:20480
	ds_read_b128 v[200:203], v213 offset:21504
	ds_read_b128 v[204:207], v213 offset:22528
	ds_read_b128 v[214:217], v213 offset:23552
	global_load_lds_dwordx4 v180, s[34:35]
	s_add_i32 m0, s57, 0x2000
	s_add_u32 s58, s34, 0x80000
	s_addc_u32 s59, s35, 0
	s_add_i32 s57, s47, s38
	global_load_lds_dwordx4 v184, s[34:35]
	s_mov_b32 m0, s57
	s_nop 0
	global_load_lds_dwordx4 v180, s[58:59]
	s_add_i32 m0, s57, 0x2000
	s_nop 0
	global_load_lds_dwordx4 v184, s[58:59]
	s_waitcnt vmcnt(6)
	s_waitcnt lgkmcnt(0)
	s_barrier
	v_mfma_f32_16x16x32_bf16 v[62:65], v[130:133], v[162:165], v[62:65]
	v_mfma_f32_16x16x32_bf16 v[58:61], v[138:141], v[162:165], v[58:61]
	v_mfma_f32_16x16x32_bf16 v[46:49], v[130:133], v[170:173], v[46:49]
	v_mfma_f32_16x16x32_bf16 v[42:45], v[138:141], v[170:173], v[42:45]
	v_mfma_f32_16x16x32_bf16 v[30:33], v[130:133], v[194:197], v[30:33]
	v_mfma_f32_16x16x32_bf16 v[26:29], v[138:141], v[194:197], v[26:29]
	v_mfma_f32_16x16x32_bf16 v[14:17], v[130:133], v[204:207], v[14:17]
	v_mfma_f32_16x16x32_bf16 v[10:13], v[138:141], v[204:207], v[10:13]
	v_mfma_f32_16x16x32_bf16 v[62:65], v[134:137], v[166:169], v[62:65]
	v_mfma_f32_16x16x32_bf16 v[58:61], v[142:145], v[166:169], v[58:61]
	v_mfma_f32_16x16x32_bf16 v[46:49], v[134:137], v[174:177], v[46:49]
	v_mfma_f32_16x16x32_bf16 v[42:45], v[142:145], v[174:177], v[42:45]
	v_mfma_f32_16x16x32_bf16 v[30:33], v[134:137], v[200:203], v[30:33]
	v_mfma_f32_16x16x32_bf16 v[26:29], v[142:145], v[200:203], v[26:29]
	v_mfma_f32_16x16x32_bf16 v[14:17], v[134:137], v[214:217], v[14:17]
	v_mfma_f32_16x16x32_bf16 v[10:13], v[142:145], v[214:217], v[10:13]
	v_mfma_f32_16x16x32_bf16 v[54:57], v[146:149], v[162:165], v[54:57]
	v_mfma_f32_16x16x32_bf16 v[50:53], v[154:157], v[162:165], v[50:53]
	v_mfma_f32_16x16x32_bf16 v[38:41], v[146:149], v[170:173], v[38:41]
	v_mfma_f32_16x16x32_bf16 v[34:37], v[154:157], v[170:173], v[34:37]
	v_mfma_f32_16x16x32_bf16 v[22:25], v[146:149], v[194:197], v[22:25]
	v_mfma_f32_16x16x32_bf16 v[18:21], v[154:157], v[194:197], v[18:21]
	v_mfma_f32_16x16x32_bf16 v[6:9], v[146:149], v[204:207], v[6:9]
	v_mfma_f32_16x16x32_bf16 v[2:5], v[154:157], v[204:207], v[2:5]
	v_mfma_f32_16x16x32_bf16 v[54:57], v[150:153], v[166:169], v[54:57]
	v_mfma_f32_16x16x32_bf16 v[50:53], v[158:161], v[166:169], v[50:53]
	v_mfma_f32_16x16x32_bf16 v[38:41], v[150:153], v[174:177], v[38:41]
	v_mfma_f32_16x16x32_bf16 v[34:37], v[158:161], v[174:177], v[34:37]
	v_mfma_f32_16x16x32_bf16 v[22:25], v[150:153], v[200:203], v[22:25]
	v_mfma_f32_16x16x32_bf16 v[18:21], v[158:161], v[200:203], v[18:21]
	v_mfma_f32_16x16x32_bf16 v[6:9], v[150:153], v[214:217], v[6:9]
	v_mfma_f32_16x16x32_bf16 v[2:5], v[158:161], v[214:217], v[2:5]
	s_barrier
; #define PG8_STAGE(bufoff, gbase, voff) do { _Pragma("unroll") for (int _i = 0; _i < 2; ++_i) \
;         __builtin_amdgcn_global_load_lds((const unsigned*)((const char*)(gbase) + (voff)[_i]), (PG8_LAS unsigned*)(lds + (bufoff) + ldsw + _i * 8192), 16, 0, 0); } while (0)
; #define PG8_LDA(dst, b, h) do { _Pragma("unroll") for (int m = 0; m < 4; ++m) _Pragma("unroll") for (int k = 0; k < 2; ++k) dst[m][k] = *(const PG8_LAS bf16x8*)(lds + PG8_SA(b, h) + aoff + m * 2048 + k * 1024); } while (0)
; #define PG8_LDB(dst, b, h) do { _Pragma("unroll") for (int n = 0; n < 2; ++n) _Pragma("unroll") for (int k = 0; k < 2; ++k) dst[n][k] = *(const PG8_LAS bf16x8*)(lds + PG8_SB(b, h) + boff + n * 2048 + k * 1024); } while (0)
; #define PG8_MMA(ai, bj, At, Bt) do { __builtin_amdgcn_s_setprio(1); _Pragma("unroll") for (int m = 0; m < 4; ++m) _Pragma("unroll") for (int n = 0; n < 2; ++n) _Pragma("unroll") for (int k = 0; k < 2; ++k) \
;         acc[ai][bj][m][n] = __builtin_amdgcn_mfma_f32_16x16x32_bf16(Bt[n][k], At[m][k], acc[ai][bj][m][n], 0, 0, 0); __builtin_amdgcn_s_setprio(0); } while (0)
; #define PG8_WAIT_V(n) asm volatile("s_waitcnt vmcnt(" #n ")" ::: "memory")
; #define PG8_WAIT_L(n) asm volatile("s_waitcnt lgkmcnt(" #n ")" ::: "memory")
; #define PG8_BAR __builtin_amdgcn_s_barrier()
; #define PG8_SCHED __builtin_amdgcn_sched_barrier(0)
; template <class Epi, class Sched, bool ALIGN_EPI = false, bool SP2 = false>
; __device__ __forceinline__ void gemm_phase(PG8_LAS unsigned char* lds, const Gemm g, const Sched& S, const Epi& E) {
;     ...
;         for (int t = 0; t < nt; t += 2) {
;             const bool last = (t == nt - 2);
;             const char* a1 = cA + (size_t)(t + 1) * kstep;
;             const char* a2 = last ? nA : cA + (size_t)(t + 2) * kstep; const char* b2 = last ? nB : cB + (size_t)(t + 2) * kstep;
;     ...
;             PG8_LDB(B0, 1, 0); PG8_LDB(B1, 1, 1); PG8_SCHED; PG8_LDA(At, 1, 0); PG8_STAGE(PG8_SA(0, 1), a2 + hstep, voffA);
;             PG8_WAIT_V(8); PG8_WAIT_L(0); PG8_BAR; PG8_MMA(0, 0, At, B0); PG8_MMA(0, 1, At, B1); PG8_BAR; PG8_SCHED;
;             PG8_LDA(At, 1, 1); PG8_STAGE(PG8_SB(1, 0), b3, voffB); PG8_STAGE(PG8_SB(1, 1), b3 + hstep, voffB); PG8_STAGE(PG8_SA(1, 0), a3, voffA);
;             PG8_WAIT_V(8); PG8_WAIT_L(0); PG8_BAR; PG8_MMA(1, 0, At, B0); PG8_MMA(1, 1, At, B1); PG8_BAR; PG8_SCHED;
	s_mov_b32 m0, s29
	s_nop 0
	global_load_lds_dwordx4 v178, s[36:37]
	s_mov_b32 m0, s39
	s_nop 0
	global_load_lds_dwordx4 v182, s[36:37]
	s_add_i32 s57, 0, 0x18000
	s_add_i32 s58, 0, 0x1c000
	v_add_u32_e32 v142, s57, v199
	v_add_u32_e32 v158, s58, v199
	ds_read_b128 v[130:133], v142
	ds_read_b128 v[134:137], v142 offset:1024
	ds_read_b128 v[138:141], v142 offset:2048
	ds_read_b128 v[142:145], v142 offset:3072
	ds_read_b128 v[146:149], v158
	ds_read_b128 v[150:153], v158 offset:1024
	ds_read_b128 v[154:157], v158 offset:2048
	ds_read_b128 v[158:161], v158 offset:3072
	s_add_u32 s36, s36, 0x80000
	s_addc_u32 s37, s37, 0
	s_mov_b32 m0, s40
	ds_read_b128 v[162:165], v213 offset:32768
	ds_read_b128 v[166:169], v213 offset:33792
	ds_read_b128 v[170:173], v213 offset:34816
	ds_read_b128 v[174:177], v213 offset:35840
	ds_read_b128 v[194:197], v213 offset:36864
	ds_read_b128 v[200:203], v213 offset:37888
	ds_read_b128 v[204:207], v213 offset:38912
	ds_read_b128 v[214:217], v213 offset:39936
	global_load_lds_dwordx4 v178, s[36:37]
	s_mov_b32 m0, s41
	s_nop 0
	global_load_lds_dwordx4 v182, s[36:37]
	s_waitcnt vmcnt(8)
	s_waitcnt lgkmcnt(0)
	s_barrier
	v_mfma_f32_16x16x32_bf16 v[126:129], v[130:133], v[162:165], v[126:129]
	v_mfma_f32_16x16x32_bf16 v[122:125], v[138:141], v[162:165], v[122:125]
	v_mfma_f32_16x16x32_bf16 v[110:113], v[130:133], v[170:173], v[110:113]
	v_mfma_f32_16x16x32_bf16 v[106:109], v[138:141], v[170:173], v[106:109]
	v_mfma_f32_16x16x32_bf16 v[94:97], v[130:133], v[194:197], v[94:97]
	v_mfma_f32_16x16x32_bf16 v[90:93], v[138:141], v[194:197], v[90:93]
	v_mfma_f32_16x16x32_bf16 v[78:81], v[130:133], v[204:207], v[78:81]
	v_mfma_f32_16x16x32_bf16 v[74:77], v[138:141], v[204:207], v[74:77]
	v_mfma_f32_16x16x32_bf16 v[126:129], v[134:137], v[166:169], v[126:129]
	v_mfma_f32_16x16x32_bf16 v[122:125], v[142:145], v[166:169], v[122:125]
	v_mfma_f32_16x16x32_bf16 v[110:113], v[134:137], v[174:177], v[110:113]
	v_mfma_f32_16x16x32_bf16 v[106:109], v[142:145], v[174:177], v[106:109]
	v_mfma_f32_16x16x32_bf16 v[94:97], v[134:137], v[200:203], v[94:97]
	v_mfma_f32_16x16x32_bf16 v[90:93], v[142:145], v[200:203], v[90:93]
	v_mfma_f32_16x16x32_bf16 v[78:81], v[134:137], v[214:217], v[78:81]
	v_mfma_f32_16x16x32_bf16 v[74:77], v[142:145], v[214:217], v[74:77]
	v_mfma_f32_16x16x32_bf16 v[118:121], v[146:149], v[162:165], v[118:121]
	v_mfma_f32_16x16x32_bf16 v[114:117], v[154:157], v[162:165], v[114:117]
	v_mfma_f32_16x16x32_bf16 v[102:105], v[146:149], v[170:173], v[102:105]
	v_mfma_f32_16x16x32_bf16 v[98:101], v[154:157], v[170:173], v[98:101]
	v_mfma_f32_16x16x32_bf16 v[86:89], v[146:149], v[194:197], v[86:89]
	v_mfma_f32_16x16x32_bf16 v[82:85], v[154:157], v[194:197], v[82:85]
	v_mfma_f32_16x16x32_bf16 v[70:73], v[146:149], v[204:207], v[70:73]
	v_mfma_f32_16x16x32_bf16 v[66:69], v[154:157], v[204:207], v[66:69]
	v_mfma_f32_16x16x32_bf16 v[118:121], v[150:153], v[166:169], v[118:121]
	v_mfma_f32_16x16x32_bf16 v[114:117], v[158:161], v[166:169], v[114:117]
	v_mfma_f32_16x16x32_bf16 v[102:105], v[150:153], v[174:177], v[102:105]
	v_mfma_f32_16x16x32_bf16 v[98:101], v[158:161], v[174:177], v[98:101]
	v_mfma_f32_16x16x32_bf16 v[86:89], v[150:153], v[200:203], v[86:89]
	v_mfma_f32_16x16x32_bf16 v[82:85], v[158:161], v[200:203], v[82:85]
	v_mfma_f32_16x16x32_bf16 v[70:73], v[150:153], v[214:217], v[70:73]
	v_mfma_f32_16x16x32_bf16 v[66:69], v[158:161], v[214:217], v[66:69]
	s_barrier
	s_add_i32 s36, s57, s38
	s_add_u32 s34, s34, 0x80
	s_addc_u32 s35, s35, 0
	s_mov_b32 m0, s36
	ds_read_b128 v[162:165], v213 offset:49152
	ds_read_b128 v[166:169], v213 offset:50176
	ds_read_b128 v[170:173], v213 offset:51200
	ds_read_b128 v[174:177], v213 offset:52224
	ds_read_b128 v[194:197], v213 offset:53248
	ds_read_b128 v[200:203], v213 offset:54272
	ds_read_b128 v[204:207], v213 offset:55296
	ds_read_b128 v[214:217], v213 offset:56320
	global_load_lds_dwordx4 v180, s[34:35]
	s_add_i32 m0, s36, 0x2000
	s_add_i32 s36, s58, s38
	global_load_lds_dwordx4 v184, s[34:35]
	s_add_u32 s34, s34, 0x80000
	s_addc_u32 s35, s35, 0
	s_mov_b32 m0, s36
	s_nop 0
	global_load_lds_dwordx4 v180, s[34:35]
	s_add_i32 m0, s36, 0x2000
	s_nop 0
	global_load_lds_dwordx4 v184, s[34:35]
	s_waitcnt vmcnt(6)
	s_waitcnt lgkmcnt(0)
	s_barrier
	v_mfma_f32_16x16x32_bf16 v[62:65], v[130:133], v[162:165], v[62:65]
	v_mfma_f32_16x16x32_bf16 v[58:61], v[138:141], v[162:165], v[58:61]
	v_mfma_f32_16x16x32_bf16 v[46:49], v[130:133], v[170:173], v[46:49]
	v_mfma_f32_16x16x32_bf16 v[42:45], v[138:141], v[170:173], v[42:45]
	v_mfma_f32_16x16x32_bf16 v[30:33], v[130:133], v[194:197], v[30:33]
	v_mfma_f32_16x16x32_bf16 v[26:29], v[138:141], v[194:197], v[26:29]
	v_mfma_f32_16x16x32_bf16 v[14:17], v[130:133], v[204:207], v[14:17]
	v_mfma_f32_16x16x32_bf16 v[10:13], v[138:141], v[204:207], v[10:13]
	v_mfma_f32_16x16x32_bf16 v[62:65], v[134:137], v[166:169], v[62:65]
	v_mfma_f32_16x16x32_bf16 v[58:61], v[142:145], v[166:169], v[58:61]
	v_mfma_f32_16x16x32_bf16 v[46:49], v[134:137], v[174:177], v[46:49]
	v_mfma_f32_16x16x32_bf16 v[42:45], v[142:145], v[174:177], v[42:45]
	v_mfma_f32_16x16x32_bf16 v[30:33], v[134:137], v[200:203], v[30:33]
	v_mfma_f32_16x16x32_bf16 v[26:29], v[142:145], v[200:203], v[26:29]
	v_mfma_f32_16x16x32_bf16 v[14:17], v[134:137], v[214:217], v[14:17]
	v_mfma_f32_16x16x32_bf16 v[10:13], v[142:145], v[214:217], v[10:13]
	v_mfma_f32_16x16x32_bf16 v[54:57], v[146:149], v[162:165], v[54:57]
	v_mfma_f32_16x16x32_bf16 v[50:53], v[154:157], v[162:165], v[50:53]
	v_mfma_f32_16x16x32_bf16 v[38:41], v[146:149], v[170:173], v[38:41]
	v_mfma_f32_16x16x32_bf16 v[34:37], v[154:157], v[170:173], v[34:37]
	v_mfma_f32_16x16x32_bf16 v[22:25], v[146:149], v[194:197], v[22:25]
	v_mfma_f32_16x16x32_bf16 v[18:21], v[154:157], v[194:197], v[18:21]
	v_mfma_f32_16x16x32_bf16 v[6:9], v[146:149], v[204:207], v[6:9]
	v_mfma_f32_16x16x32_bf16 v[2:5], v[154:157], v[204:207], v[2:5]
	v_mfma_f32_16x16x32_bf16 v[54:57], v[150:153], v[166:169], v[54:57]
	v_mfma_f32_16x16x32_bf16 v[50:53], v[158:161], v[166:169], v[50:53]
	v_mfma_f32_16x16x32_bf16 v[38:41], v[150:153], v[174:177], v[38:41]
	v_mfma_f32_16x16x32_bf16 v[34:37], v[158:161], v[174:177], v[34:37]
	v_mfma_f32_16x16x32_bf16 v[22:25], v[150:153], v[200:203], v[22:25]
	v_mfma_f32_16x16x32_bf16 v[18:21], v[158:161], v[200:203], v[18:21]
	v_mfma_f32_16x16x32_bf16 v[6:9], v[150:153], v[214:217], v[6:9]
	v_mfma_f32_16x16x32_bf16 v[2:5], v[158:161], v[214:217], v[2:5]
	s_barrier
	s_add_i32 s56, s56, 2
	s_add_u32 s30, s30, 0x100
	s_addc_u32 s31, s31, 0
	s_add_u32 s52, s52, 0x100
	s_addc_u32 s53, s53, 0
	s_cmp_gt_u32 s56, 29
	s_cbranch_scc0 .LBB0_884
	s_and_b64 vcc, exec, s[10:11]
	s_cbranch_vccz .LBB0_887
	s_barrier

; #define PG8_STAGE(bufoff, gbase, voff) do { _Pragma("unroll") for (int _i = 0; _i < 2; ++_i) \
;         __builtin_amdgcn_global_load_lds((const unsigned*)((const char*)(gbase) + (voff)[_i]), (PG8_LAS unsigned*)(lds + (bufoff) + ldsw + _i * 8192), 16, 0, 0); } while (0)
; #define PG8_LDA(dst, b, h) do { _Pragma("unroll") for (int m = 0; m < 4; ++m) _Pragma("unroll") for (int k = 0; k < 2; ++k) dst[m][k] = *(const PG8_LAS bf16x8*)(lds + PG8_SA(b, h) + aoff + m * 2048 + k * 1024); } while (0)
; #define PG8_LDB(dst, b, h) do { _Pragma("unroll") for (int n = 0; n < 2; ++n) _Pragma("unroll") for (int k = 0; k < 2; ++k) dst[n][k] = *(const PG8_LAS bf16x8*)(lds + PG8_SB(b, h) + boff + n * 2048 + k * 1024); } while (0)
; #define PG8_MMA(ai, bj, At, Bt) do { __builtin_amdgcn_s_setprio(1); _Pragma("unroll") for (int m = 0; m < 4; ++m) _Pragma("unroll") for (int n = 0; n < 2; ++n) _Pragma("unroll") for (int k = 0; k < 2; ++k) \
;         acc[ai][bj][m][n] = __builtin_amdgcn_mfma_f32_16x16x32_bf16(Bt[n][k], At[m][k], acc[ai][bj][m][n], 0, 0, 0); __builtin_amdgcn_s_setprio(0); } while (0)
; #define PG8_WAIT_V(n) asm volatile("s_waitcnt vmcnt(" #n ")" ::: "memory")
; #define PG8_WAIT_L(n) asm volatile("s_waitcnt lgkmcnt(" #n ")" ::: "memory")
; #define PG8_BAR __builtin_amdgcn_s_barrier()
; #define PG8_SCHED __builtin_amdgcn_sched_barrier(0)
; template <class Epi, class Sched, bool ALIGN_EPI = false, bool SP2 = false>
; __device__ __forceinline__ void gemm_phase(PG8_LAS unsigned char* lds, const Gemm g, const Sched& S, const Epi& E) {
;     ...
;             PG8_LDB(B0, 0, 0); PG8_LDB(B1, 0, 1); PG8_SCHED; PG8_LDA(At, 0, 0); PG8_STAGE(PG8_SA(1, 1), a1 + hstep, voffA);
;             PG8_WAIT_V(8); PG8_WAIT_L(0); PG8_BAR; PG8_MMA(0, 0, At, B0); PG8_MMA(0, 1, At, B1); PG8_BAR; PG8_SCHED;
;             PG8_LDA(At, 0, 1); PG8_STAGE(PG8_SB(0, 0), b2, voffB); PG8_STAGE(PG8_SB(0, 1), b2 + hstep, voffB); PG8_STAGE(PG8_SA(0, 0), a2, voffA);
;             PG8_WAIT_V(8); PG8_WAIT_L(0); PG8_BAR; PG8_MMA(1, 0, At, B0); PG8_MMA(1, 1, At, B1); PG8_BAR; PG8_SCHED;
.LBB0_959:
	s_add_u32 s30, s28, 0xfff00000
	s_addc_u32 s31, s29, -1
	s_mov_b32 m0, s41
	s_nop 0
	global_load_lds_dwordx4 v138, s[30:31]
	s_mov_b32 m0, s42
	s_nop 0
	global_load_lds_dwordx4 v142, s[30:31]
	s_add_u32 s30, s30, 0x80
	s_addc_u32 s31, s31, 0
	ds_read_b128 v[130:133], v164
	ds_read_b128 v[134:137], v164 offset:1024
	ds_read_b128 v[154:157], v164 offset:2048
	ds_read_b128 v[158:161], v164 offset:3072
	ds_read_b128 v[168:171], v165
	ds_read_b128 v[172:175], v165 offset:1024
	ds_read_b128 v[176:179], v165 offset:2048
	ds_read_b128 v[180:183], v165 offset:3072
	s_cmp_eq_u32 s51, 60
	s_cselect_b32 s35, s13, s31
	s_cselect_b32 s34, s47, s30
	s_cselect_b32 s31, s11, s50
	s_cselect_b32 s30, s48, s49
	s_add_i32 m0, s27, 0xc000
	ds_read_b128 v[184:187], v166
	ds_read_b128 v[188:191], v166 offset:1024
	ds_read_b128 v[192:195], v166 offset:2048
	ds_read_b128 v[200:203], v166 offset:3072
	ds_read_b128 v[204:207], v166 offset:4096
	ds_read_b128 v[208:211], v166 offset:5120
	ds_read_b128 v[212:215], v166 offset:6144
	ds_read_b128 v[216:219], v166 offset:7168
	global_load_lds_dwordx4 v146, s[28:29]
	s_add_i32 m0, s27, 0xe000
	s_nop 0
	global_load_lds_dwordx4 v148, s[28:29]
	s_waitcnt vmcnt(8)
	s_waitcnt lgkmcnt(0)
	s_barrier
	v_mfma_f32_16x16x32_bf16 v[126:129], v[130:133], v[184:187], v[126:129]
	v_mfma_f32_16x16x32_bf16 v[122:125], v[154:157], v[184:187], v[122:125]
	v_mfma_f32_16x16x32_bf16 v[118:121], v[130:133], v[192:195], v[118:121]
	v_mfma_f32_16x16x32_bf16 v[114:117], v[154:157], v[192:195], v[114:117]
	v_mfma_f32_16x16x32_bf16 v[110:113], v[130:133], v[204:207], v[110:113]
	v_mfma_f32_16x16x32_bf16 v[102:105], v[154:157], v[204:207], v[102:105]
	v_mfma_f32_16x16x32_bf16 v[82:85], v[130:133], v[212:215], v[82:85]
	v_mfma_f32_16x16x32_bf16 v[74:77], v[154:157], v[212:215], v[74:77]
	v_mfma_f32_16x16x32_bf16 v[126:129], v[134:137], v[188:191], v[126:129]
	v_mfma_f32_16x16x32_bf16 v[122:125], v[158:161], v[188:191], v[122:125]
	v_mfma_f32_16x16x32_bf16 v[118:121], v[134:137], v[200:203], v[118:121]
	v_mfma_f32_16x16x32_bf16 v[114:117], v[158:161], v[200:203], v[114:117]
	v_mfma_f32_16x16x32_bf16 v[110:113], v[134:137], v[208:211], v[110:113]
	v_mfma_f32_16x16x32_bf16 v[102:105], v[158:161], v[208:211], v[102:105]
	v_mfma_f32_16x16x32_bf16 v[82:85], v[134:137], v[216:219], v[82:85]
	v_mfma_f32_16x16x32_bf16 v[74:77], v[158:161], v[216:219], v[74:77]
	v_mfma_f32_16x16x32_bf16 v[106:109], v[168:171], v[184:187], v[106:109]
	v_mfma_f32_16x16x32_bf16 v[98:101], v[176:179], v[184:187], v[98:101]
	v_mfma_f32_16x16x32_bf16 v[94:97], v[168:171], v[192:195], v[94:97]
	v_mfma_f32_16x16x32_bf16 v[90:93], v[176:179], v[192:195], v[90:93]
	v_mfma_f32_16x16x32_bf16 v[86:89], v[168:171], v[204:207], v[86:89]
	v_mfma_f32_16x16x32_bf16 v[78:81], v[176:179], v[204:207], v[78:81]
	v_mfma_f32_16x16x32_bf16 v[70:73], v[168:171], v[212:215], v[70:73]
	v_mfma_f32_16x16x32_bf16 v[66:69], v[176:179], v[212:215], v[66:69]
	v_mfma_f32_16x16x32_bf16 v[106:109], v[172:175], v[188:191], v[106:109]
	v_mfma_f32_16x16x32_bf16 v[98:101], v[180:183], v[188:191], v[98:101]
	v_mfma_f32_16x16x32_bf16 v[94:97], v[172:175], v[200:203], v[94:97]
	v_mfma_f32_16x16x32_bf16 v[90:93], v[180:183], v[200:203], v[90:93]
	v_mfma_f32_16x16x32_bf16 v[86:89], v[172:175], v[208:211], v[86:89]
	v_mfma_f32_16x16x32_bf16 v[78:81], v[180:183], v[208:211], v[78:81]
	v_mfma_f32_16x16x32_bf16 v[70:73], v[172:175], v[216:219], v[70:73]
	v_mfma_f32_16x16x32_bf16 v[66:69], v[180:183], v[216:219], v[66:69]
	s_barrier
	s_add_i32 s52, s44, s36
	s_mov_b32 m0, s52
	ds_read_b128 v[184:187], v166 offset:16384
	ds_read_b128 v[188:191], v166 offset:17408
	ds_read_b128 v[192:195], v166 offset:18432
	ds_read_b128 v[200:203], v166 offset:19456
	ds_read_b128 v[204:207], v166 offset:20480
	ds_read_b128 v[208:211], v166 offset:21504
	ds_read_b128 v[212:215], v166 offset:22528
	ds_read_b128 v[216:219], v166 offset:23552
	global_load_lds_dwordx4 v140, s[30:31]
	s_add_i32 m0, s52, 0x2000
	s_add_u32 s52, s30, 0x100000
	s_addc_u32 s53, s31, 0
	s_add_i32 s54, s45, s36
	global_load_lds_dwordx4 v144, s[30:31]
	s_mov_b32 m0, s54
	s_nop 0
	global_load_lds_dwordx4 v140, s[52:53]
	s_add_i32 m0, s54, 0x2000
	s_nop 0
	global_load_lds_dwordx4 v144, s[52:53]
	s_waitcnt vmcnt(6)
	s_waitcnt lgkmcnt(0)
	s_barrier
	v_mfma_f32_16x16x32_bf16 v[62:65], v[130:133], v[184:187], v[62:65]
	v_mfma_f32_16x16x32_bf16 v[58:61], v[154:157], v[184:187], v[58:61]
	v_mfma_f32_16x16x32_bf16 v[50:53], v[130:133], v[192:195], v[50:53]
	v_mfma_f32_16x16x32_bf16 v[42:45], v[154:157], v[192:195], v[42:45]
	v_mfma_f32_16x16x32_bf16 v[34:37], v[130:133], v[204:207], v[34:37]
	v_mfma_f32_16x16x32_bf16 v[26:29], v[154:157], v[204:207], v[26:29]
	v_mfma_f32_16x16x32_bf16 v[18:21], v[130:133], v[212:215], v[18:21]
	v_mfma_f32_16x16x32_bf16 v[10:13], v[154:157], v[212:215], v[10:13]
	v_mfma_f32_16x16x32_bf16 v[62:65], v[134:137], v[188:191], v[62:65]
	v_mfma_f32_16x16x32_bf16 v[58:61], v[158:161], v[188:191], v[58:61]
	v_mfma_f32_16x16x32_bf16 v[50:53], v[134:137], v[200:203], v[50:53]
	v_mfma_f32_16x16x32_bf16 v[42:45], v[158:161], v[200:203], v[42:45]
	v_mfma_f32_16x16x32_bf16 v[34:37], v[134:137], v[208:211], v[34:37]
	v_mfma_f32_16x16x32_bf16 v[26:29], v[158:161], v[208:211], v[26:29]
	v_mfma_f32_16x16x32_bf16 v[18:21], v[134:137], v[216:219], v[18:21]
	v_mfma_f32_16x16x32_bf16 v[10:13], v[158:161], v[216:219], v[10:13]
	v_mfma_f32_16x16x32_bf16 v[54:57], v[168:171], v[184:187], v[54:57]
	v_mfma_f32_16x16x32_bf16 v[46:49], v[176:179], v[184:187], v[46:49]
	v_mfma_f32_16x16x32_bf16 v[38:41], v[168:171], v[192:195], v[38:41]
	v_mfma_f32_16x16x32_bf16 v[30:33], v[176:179], v[192:195], v[30:33]
	v_mfma_f32_16x16x32_bf16 v[22:25], v[168:171], v[204:207], v[22:25]
	v_mfma_f32_16x16x32_bf16 v[14:17], v[176:179], v[204:207], v[14:17]
	v_mfma_f32_16x16x32_bf16 v[6:9], v[168:171], v[212:215], v[6:9]
	v_mfma_f32_16x16x32_bf16 v[2:5], v[176:179], v[212:215], v[2:5]
	v_mfma_f32_16x16x32_bf16 v[54:57], v[172:175], v[188:191], v[54:57]
	v_mfma_f32_16x16x32_bf16 v[46:49], v[180:183], v[188:191], v[46:49]
	v_mfma_f32_16x16x32_bf16 v[38:41], v[172:175], v[200:203], v[38:41]
	v_mfma_f32_16x16x32_bf16 v[30:33], v[180:183], v[200:203], v[30:33]
	v_mfma_f32_16x16x32_bf16 v[22:25], v[172:175], v[208:211], v[22:25]
	v_mfma_f32_16x16x32_bf16 v[14:17], v[180:183], v[208:211], v[14:17]
	v_mfma_f32_16x16x32_bf16 v[6:9], v[172:175], v[216:219], v[6:9]
	v_mfma_f32_16x16x32_bf16 v[2:5], v[180:183], v[216:219], v[2:5]
	s_barrier
; #define PG8_STAGE(bufoff, gbase, voff) do { _Pragma("unroll") for (int _i = 0; _i < 2; ++_i) \
;         __builtin_amdgcn_global_load_lds((const unsigned*)((const char*)(gbase) + (voff)[_i]), (PG8_LAS unsigned*)(lds + (bufoff) + ldsw + _i * 8192), 16, 0, 0); } while (0)
; #define PG8_LDA(dst, b, h) do { _Pragma("unroll") for (int m = 0; m < 4; ++m) _Pragma("unroll") for (int k = 0; k < 2; ++k) dst[m][k] = *(const PG8_LAS bf16x8*)(lds + PG8_SA(b, h) + aoff + m * 2048 + k * 1024); } while (0)
; #define PG8_LDB(dst, b, h) do { _Pragma("unroll") for (int n = 0; n < 2; ++n) _Pragma("unroll") for (int k = 0; k < 2; ++k) dst[n][k] = *(const PG8_LAS bf16x8*)(lds + PG8_SB(b, h) + boff + n * 2048 + k * 1024); } while (0)
; #define PG8_MMA(ai, bj, At, Bt) do { __builtin_amdgcn_s_setprio(1); _Pragma("unroll") for (int m = 0; m < 4; ++m) _Pragma("unroll") for (int n = 0; n < 2; ++n) _Pragma("unroll") for (int k = 0; k < 2; ++k) \
;         acc[ai][bj][m][n] = __builtin_amdgcn_mfma_f32_16x16x32_bf16(Bt[n][k], At[m][k], acc[ai][bj][m][n], 0, 0, 0); __builtin_amdgcn_s_setprio(0); } while (0)
; #define PG8_WAIT_V(n) asm volatile("s_waitcnt vmcnt(" #n ")" ::: "memory")
; #define PG8_WAIT_L(n) asm volatile("s_waitcnt lgkmcnt(" #n ")" ::: "memory")
; #define PG8_BAR __builtin_amdgcn_s_barrier()
; #define PG8_SCHED __builtin_amdgcn_sched_barrier(0)
; template <class Epi, class Sched, bool ALIGN_EPI = false, bool SP2 = false>
; __device__ __forceinline__ void gemm_phase(PG8_LAS unsigned char* lds, const Gemm g, const Sched& S, const Epi& E) {
;     ...
;         for (int t = 0; t < nt; t += 2) {
;             const bool last = (t == nt - 2);
;             const char* a1 = cA + (size_t)(t + 1) * kstep;
;             const char* a2 = last ? nA : cA + (size_t)(t + 2) * kstep; const char* b2 = last ? nB : cB + (size_t)(t + 2) * kstep;
;     ...
;             PG8_LDB(B0, 1, 0); PG8_LDB(B1, 1, 1); PG8_SCHED; PG8_LDA(At, 1, 0); PG8_STAGE(PG8_SA(0, 1), a2 + hstep, voffA);
;             PG8_WAIT_V(8); PG8_WAIT_L(0); PG8_BAR; PG8_MMA(0, 0, At, B0); PG8_MMA(0, 1, At, B1); PG8_BAR; PG8_SCHED;
;             PG8_LDA(At, 1, 1); PG8_STAGE(PG8_SB(1, 0), b3, voffB); PG8_STAGE(PG8_SB(1, 1), b3 + hstep, voffB); PG8_STAGE(PG8_SA(1, 0), a3, voffA);
;             PG8_WAIT_V(8); PG8_WAIT_L(0); PG8_BAR; PG8_MMA(1, 0, At, B0); PG8_MMA(1, 1, At, B1); PG8_BAR; PG8_SCHED;
	s_mov_b32 m0, s27
	s_nop 0
	global_load_lds_dwordx4 v138, s[34:35]
	s_mov_b32 m0, s37
	s_nop 0
	global_load_lds_dwordx4 v142, s[34:35]
	s_add_i32 s52, 0, 0x18000
	s_add_i32 s53, 0, 0x1c000
	v_add_u32_e32 v158, s52, v162
	v_add_u32_e32 v167, s53, v162
	ds_read_b128 v[130:133], v158
	ds_read_b128 v[134:137], v158 offset:1024
	ds_read_b128 v[154:157], v158 offset:2048
	ds_read_b128 v[158:161], v158 offset:3072
	ds_read_b128 v[168:171], v167
	ds_read_b128 v[172:175], v167 offset:1024
	ds_read_b128 v[176:179], v167 offset:2048
	ds_read_b128 v[180:183], v167 offset:3072
	s_add_u32 s34, s34, 0x100000
	s_addc_u32 s35, s35, 0
	s_mov_b32 m0, s38
	ds_read_b128 v[184:187], v166 offset:32768
	ds_read_b128 v[188:191], v166 offset:33792
	ds_read_b128 v[192:195], v166 offset:34816
	ds_read_b128 v[200:203], v166 offset:35840
	ds_read_b128 v[204:207], v166 offset:36864
	ds_read_b128 v[208:211], v166 offset:37888
	ds_read_b128 v[212:215], v166 offset:38912
	ds_read_b128 v[216:219], v166 offset:39936
	global_load_lds_dwordx4 v138, s[34:35]
	s_mov_b32 m0, s39
	s_nop 0
	global_load_lds_dwordx4 v142, s[34:35]
	s_waitcnt vmcnt(8)
	s_waitcnt lgkmcnt(0)
	s_barrier
	v_mfma_f32_16x16x32_bf16 v[126:129], v[130:133], v[184:187], v[126:129]
	v_mfma_f32_16x16x32_bf16 v[122:125], v[154:157], v[184:187], v[122:125]
	v_mfma_f32_16x16x32_bf16 v[118:121], v[130:133], v[192:195], v[118:121]
	v_mfma_f32_16x16x32_bf16 v[114:117], v[154:157], v[192:195], v[114:117]
	v_mfma_f32_16x16x32_bf16 v[110:113], v[130:133], v[204:207], v[110:113]
	v_mfma_f32_16x16x32_bf16 v[102:105], v[154:157], v[204:207], v[102:105]
	v_mfma_f32_16x16x32_bf16 v[82:85], v[130:133], v[212:215], v[82:85]
	v_mfma_f32_16x16x32_bf16 v[74:77], v[154:157], v[212:215], v[74:77]
	v_mfma_f32_16x16x32_bf16 v[126:129], v[134:137], v[188:191], v[126:129]
	v_mfma_f32_16x16x32_bf16 v[122:125], v[158:161], v[188:191], v[122:125]
	v_mfma_f32_16x16x32_bf16 v[118:121], v[134:137], v[200:203], v[118:121]
	v_mfma_f32_16x16x32_bf16 v[114:117], v[158:161], v[200:203], v[114:117]
	v_mfma_f32_16x16x32_bf16 v[110:113], v[134:137], v[208:211], v[110:113]
	v_mfma_f32_16x16x32_bf16 v[102:105], v[158:161], v[208:211], v[102:105]
	v_mfma_f32_16x16x32_bf16 v[82:85], v[134:137], v[216:219], v[82:85]
	v_mfma_f32_16x16x32_bf16 v[74:77], v[158:161], v[216:219], v[74:77]
	v_mfma_f32_16x16x32_bf16 v[106:109], v[168:171], v[184:187], v[106:109]
	v_mfma_f32_16x16x32_bf16 v[98:101], v[176:179], v[184:187], v[98:101]
	v_mfma_f32_16x16x32_bf16 v[94:97], v[168:171], v[192:195], v[94:97]
	v_mfma_f32_16x16x32_bf16 v[90:93], v[176:179], v[192:195], v[90:93]
	v_mfma_f32_16x16x32_bf16 v[86:89], v[168:171], v[204:207], v[86:89]
	v_mfma_f32_16x16x32_bf16 v[78:81], v[176:179], v[204:207], v[78:81]
	v_mfma_f32_16x16x32_bf16 v[70:73], v[168:171], v[212:215], v[70:73]
	v_mfma_f32_16x16x32_bf16 v[66:69], v[176:179], v[212:215], v[66:69]
	v_mfma_f32_16x16x32_bf16 v[106:109], v[172:175], v[188:191], v[106:109]
	v_mfma_f32_16x16x32_bf16 v[98:101], v[180:183], v[188:191], v[98:101]
	v_mfma_f32_16x16x32_bf16 v[94:97], v[172:175], v[200:203], v[94:97]
	v_mfma_f32_16x16x32_bf16 v[90:93], v[180:183], v[200:203], v[90:93]
	v_mfma_f32_16x16x32_bf16 v[86:89], v[172:175], v[208:211], v[86:89]
	v_mfma_f32_16x16x32_bf16 v[78:81], v[180:183], v[208:211], v[78:81]
	v_mfma_f32_16x16x32_bf16 v[70:73], v[172:175], v[216:219], v[70:73]
	v_mfma_f32_16x16x32_bf16 v[66:69], v[180:183], v[216:219], v[66:69]
	s_barrier
	s_add_i32 s34, s52, s36
	s_add_u32 s30, s30, 0x80
	s_addc_u32 s31, s31, 0
	s_mov_b32 m0, s34
	ds_read_b128 v[184:187], v166 offset:49152
	ds_read_b128 v[188:191], v166 offset:50176
	ds_read_b128 v[192:195], v166 offset:51200
	ds_read_b128 v[200:203], v166 offset:52224
	ds_read_b128 v[204:207], v166 offset:53248
	ds_read_b128 v[208:211], v166 offset:54272
	ds_read_b128 v[212:215], v166 offset:55296
	ds_read_b128 v[216:219], v166 offset:56320
	global_load_lds_dwordx4 v140, s[30:31]
	s_add_i32 m0, s34, 0x2000
	s_add_i32 s34, s53, s36
	global_load_lds_dwordx4 v144, s[30:31]
	s_add_u32 s30, s30, 0x100000
	s_addc_u32 s31, s31, 0
	s_mov_b32 m0, s34
	s_nop 0
	global_load_lds_dwordx4 v140, s[30:31]
	s_add_i32 m0, s34, 0x2000
	s_nop 0
	global_load_lds_dwordx4 v144, s[30:31]
	s_waitcnt vmcnt(6)
	s_waitcnt lgkmcnt(0)
	s_barrier
	v_mfma_f32_16x16x32_bf16 v[62:65], v[130:133], v[184:187], v[62:65]
	v_mfma_f32_16x16x32_bf16 v[58:61], v[154:157], v[184:187], v[58:61]
	v_mfma_f32_16x16x32_bf16 v[50:53], v[130:133], v[192:195], v[50:53]
	v_mfma_f32_16x16x32_bf16 v[42:45], v[154:157], v[192:195], v[42:45]
	v_mfma_f32_16x16x32_bf16 v[34:37], v[130:133], v[204:207], v[34:37]
	v_mfma_f32_16x16x32_bf16 v[26:29], v[154:157], v[204:207], v[26:29]
	v_mfma_f32_16x16x32_bf16 v[18:21], v[130:133], v[212:215], v[18:21]
	v_mfma_f32_16x16x32_bf16 v[10:13], v[154:157], v[212:215], v[10:13]
	v_mfma_f32_16x16x32_bf16 v[62:65], v[134:137], v[188:191], v[62:65]
	v_mfma_f32_16x16x32_bf16 v[58:61], v[158:161], v[188:191], v[58:61]
	v_mfma_f32_16x16x32_bf16 v[50:53], v[134:137], v[200:203], v[50:53]
	v_mfma_f32_16x16x32_bf16 v[42:45], v[158:161], v[200:203], v[42:45]
	v_mfma_f32_16x16x32_bf16 v[34:37], v[134:137], v[208:211], v[34:37]
	v_mfma_f32_16x16x32_bf16 v[26:29], v[158:161], v[208:211], v[26:29]
	v_mfma_f32_16x16x32_bf16 v[18:21], v[134:137], v[216:219], v[18:21]
	v_mfma_f32_16x16x32_bf16 v[10:13], v[158:161], v[216:219], v[10:13]
	v_mfma_f32_16x16x32_bf16 v[54:57], v[168:171], v[184:187], v[54:57]
	v_mfma_f32_16x16x32_bf16 v[46:49], v[176:179], v[184:187], v[46:49]
	v_mfma_f32_16x16x32_bf16 v[38:41], v[168:171], v[192:195], v[38:41]
	v_mfma_f32_16x16x32_bf16 v[30:33], v[176:179], v[192:195], v[30:33]
	v_mfma_f32_16x16x32_bf16 v[22:25], v[168:171], v[204:207], v[22:25]
	v_mfma_f32_16x16x32_bf16 v[14:17], v[176:179], v[204:207], v[14:17]
	v_mfma_f32_16x16x32_bf16 v[6:9], v[168:171], v[212:215], v[6:9]
	v_mfma_f32_16x16x32_bf16 v[2:5], v[176:179], v[212:215], v[2:5]
	v_mfma_f32_16x16x32_bf16 v[54:57], v[172:175], v[188:191], v[54:57]
	v_mfma_f32_16x16x32_bf16 v[46:49], v[180:183], v[188:191], v[46:49]
	v_mfma_f32_16x16x32_bf16 v[38:41], v[172:175], v[200:203], v[38:41]
	v_mfma_f32_16x16x32_bf16 v[30:33], v[180:183], v[200:203], v[30:33]
	v_mfma_f32_16x16x32_bf16 v[22:25], v[172:175], v[208:211], v[22:25]
	v_mfma_f32_16x16x32_bf16 v[14:17], v[180:183], v[208:211], v[14:17]
	v_mfma_f32_16x16x32_bf16 v[6:9], v[172:175], v[216:219], v[6:9]
	v_mfma_f32_16x16x32_bf16 v[2:5], v[180:183], v[216:219], v[2:5]
	s_barrier
	s_add_i32 s51, s51, 2
	s_add_u32 s28, s28, 0x100
	s_addc_u32 s29, s29, 0
	s_add_u32 s49, s49, 0x100
	s_addc_u32 s50, s50, 0
	s_cmp_gt_u32 s51, 61
	s_cbranch_scc0 .LBB0_959
	s_and_b64 vcc, exec, s[8:9]
	s_cbranch_vccz .LBB0_962
	s_barrier

; #define PG8_STAGE(bufoff, gbase, voff) do { _Pragma("unroll") for (int _i = 0; _i < 2; ++_i) \
;         __builtin_amdgcn_global_load_lds((const unsigned*)((const char*)(gbase) + (voff)[_i]), (PG8_LAS unsigned*)(lds + (bufoff) + ldsw + _i * 8192), 16, 0, 0); } while (0)
; #define PG8_LDA(dst, b, h) do { _Pragma("unroll") for (int m = 0; m < 4; ++m) _Pragma("unroll") for (int k = 0; k < 2; ++k) dst[m][k] = *(const PG8_LAS bf16x8*)(lds + PG8_SA(b, h) + aoff + m * 2048 + k * 1024); } while (0)
; #define PG8_LDB(dst, b, h) do { _Pragma("unroll") for (int n = 0; n < 2; ++n) _Pragma("unroll") for (int k = 0; k < 2; ++k) dst[n][k] = *(const PG8_LAS bf16x8*)(lds + PG8_SB(b, h) + boff + n * 2048 + k * 1024); } while (0)
; #define PG8_MMA(ai, bj, At, Bt) do { __builtin_amdgcn_s_setprio(1); _Pragma("unroll") for (int m = 0; m < 4; ++m) _Pragma("unroll") for (int n = 0; n < 2; ++n) _Pragma("unroll") for (int k = 0; k < 2; ++k) \
;         acc[ai][bj][m][n] = __builtin_amdgcn_mfma_f32_16x16x32_bf16(Bt[n][k], At[m][k], acc[ai][bj][m][n], 0, 0, 0); __builtin_amdgcn_s_setprio(0); } while (0)
; #define PG8_WAIT_V(n) asm volatile("s_waitcnt vmcnt(" #n ")" ::: "memory")
; #define PG8_WAIT_L(n) asm volatile("s_waitcnt lgkmcnt(" #n ")" ::: "memory")
; #define PG8_BAR __builtin_amdgcn_s_barrier()
; #define PG8_SCHED __builtin_amdgcn_sched_barrier(0)
; template <class Epi, class Sched, bool ALIGN_EPI = false, bool SP2 = false>
; __device__ __forceinline__ void gemm_phase(PG8_LAS unsigned char* lds, const Gemm g, const Sched& S, const Epi& E) {
;     ...
;             PG8_LDB(B0, 0, 0); PG8_LDB(B1, 0, 1); PG8_SCHED; PG8_LDA(At, 0, 0); PG8_STAGE(PG8_SA(1, 1), a1 + hstep, voffA);
;             PG8_WAIT_V(8); PG8_WAIT_L(0); PG8_BAR; PG8_MMA(0, 0, At, B0); PG8_MMA(0, 1, At, B1); PG8_BAR; PG8_SCHED;
;             PG8_LDA(At, 0, 1); PG8_STAGE(PG8_SB(0, 0), b2, voffB); PG8_STAGE(PG8_SB(0, 1), b2 + hstep, voffB); PG8_STAGE(PG8_SA(0, 0), a2, voffA);
;             PG8_WAIT_V(8); PG8_WAIT_L(0); PG8_BAR; PG8_MMA(1, 0, At, B0); PG8_MMA(1, 1, At, B1); PG8_BAR; PG8_SCHED;
.LBB0_1081:
	s_add_u32 s34, s30, 0xfff00000
	s_addc_u32 s35, s31, -1
	s_mov_b32 m0, s44
	s_nop 0
	global_load_lds_dwordx4 v136, s[34:35]
	s_mov_b32 m0, s45
	s_nop 0
	global_load_lds_dwordx4 v132, s[34:35]
	s_add_u32 s34, s34, 0x80
	s_addc_u32 s35, s35, 0
	ds_read_b128 v[154:157], v150
	ds_read_b128 v[158:161], v150 offset:1024
	ds_read_b128 v[162:165], v150 offset:2048
	ds_read_b128 v[166:169], v150 offset:3072
	ds_read_b128 v[170:173], v151
	ds_read_b128 v[174:177], v151 offset:1024
	ds_read_b128 v[178:181], v151 offset:2048
	ds_read_b128 v[182:185], v151 offset:3072
	s_cmp_eq_u32 s55, 60
	s_cselect_b32 s37, s15, s35
	s_cselect_b32 s36, s51, s34
	s_cselect_b32 s35, s13, s54
	s_cselect_b32 s34, s52, s53
	s_add_i32 m0, s29, 0xc000
	ds_read_b128 v[186:189], v152
	ds_read_b128 v[190:193], v152 offset:1024
	ds_read_b128 v[194:197], v152 offset:2048
	ds_read_b128 v[200:203], v152 offset:3072
	ds_read_b128 v[204:207], v152 offset:4096
	ds_read_b128 v[208:211], v152 offset:5120
	ds_read_b128 v[212:215], v152 offset:6144
	ds_read_b128 v[216:219], v152 offset:7168
	global_load_lds_dwordx4 v138, s[30:31]
	s_add_i32 m0, s29, 0xe000
	s_nop 0
	global_load_lds_dwordx4 v140, s[30:31]
	s_waitcnt vmcnt(8)
	s_waitcnt lgkmcnt(0)
	s_barrier
	v_mfma_f32_16x16x32_bf16 v[126:129], v[154:157], v[186:189], v[126:129]
	v_mfma_f32_16x16x32_bf16 v[122:125], v[162:165], v[186:189], v[122:125]
	v_mfma_f32_16x16x32_bf16 v[110:113], v[154:157], v[194:197], v[110:113]
	v_mfma_f32_16x16x32_bf16 v[106:109], v[162:165], v[194:197], v[106:109]
	v_mfma_f32_16x16x32_bf16 v[94:97], v[154:157], v[204:207], v[94:97]
	v_mfma_f32_16x16x32_bf16 v[90:93], v[162:165], v[204:207], v[90:93]
	v_mfma_f32_16x16x32_bf16 v[78:81], v[154:157], v[212:215], v[78:81]
	v_mfma_f32_16x16x32_bf16 v[74:77], v[162:165], v[212:215], v[74:77]
	v_mfma_f32_16x16x32_bf16 v[126:129], v[158:161], v[190:193], v[126:129]
	v_mfma_f32_16x16x32_bf16 v[122:125], v[166:169], v[190:193], v[122:125]
	v_mfma_f32_16x16x32_bf16 v[110:113], v[158:161], v[200:203], v[110:113]
	v_mfma_f32_16x16x32_bf16 v[106:109], v[166:169], v[200:203], v[106:109]
	v_mfma_f32_16x16x32_bf16 v[94:97], v[158:161], v[208:211], v[94:97]
	v_mfma_f32_16x16x32_bf16 v[90:93], v[166:169], v[208:211], v[90:93]
	v_mfma_f32_16x16x32_bf16 v[78:81], v[158:161], v[216:219], v[78:81]
	v_mfma_f32_16x16x32_bf16 v[74:77], v[166:169], v[216:219], v[74:77]
	v_mfma_f32_16x16x32_bf16 v[118:121], v[170:173], v[186:189], v[118:121]
	v_mfma_f32_16x16x32_bf16 v[114:117], v[178:181], v[186:189], v[114:117]
	v_mfma_f32_16x16x32_bf16 v[102:105], v[170:173], v[194:197], v[102:105]
	v_mfma_f32_16x16x32_bf16 v[98:101], v[178:181], v[194:197], v[98:101]
	v_mfma_f32_16x16x32_bf16 v[86:89], v[170:173], v[204:207], v[86:89]
	v_mfma_f32_16x16x32_bf16 v[82:85], v[178:181], v[204:207], v[82:85]
	v_mfma_f32_16x16x32_bf16 v[70:73], v[170:173], v[212:215], v[70:73]
	v_mfma_f32_16x16x32_bf16 v[66:69], v[178:181], v[212:215], v[66:69]
	v_mfma_f32_16x16x32_bf16 v[118:121], v[174:177], v[190:193], v[118:121]
	v_mfma_f32_16x16x32_bf16 v[114:117], v[182:185], v[190:193], v[114:117]
	v_mfma_f32_16x16x32_bf16 v[102:105], v[174:177], v[200:203], v[102:105]
	v_mfma_f32_16x16x32_bf16 v[98:101], v[182:185], v[200:203], v[98:101]
	v_mfma_f32_16x16x32_bf16 v[86:89], v[174:177], v[208:211], v[86:89]
	v_mfma_f32_16x16x32_bf16 v[82:85], v[182:185], v[208:211], v[82:85]
	v_mfma_f32_16x16x32_bf16 v[70:73], v[174:177], v[216:219], v[70:73]
	v_mfma_f32_16x16x32_bf16 v[66:69], v[182:185], v[216:219], v[66:69]
	s_barrier
	s_add_i32 s56, s47, s33
	s_mov_b32 m0, s56
	ds_read_b128 v[186:189], v152 offset:16384
	ds_read_b128 v[190:193], v152 offset:17408
	ds_read_b128 v[194:197], v152 offset:18432
	ds_read_b128 v[200:203], v152 offset:19456
	ds_read_b128 v[204:207], v152 offset:20480
	ds_read_b128 v[208:211], v152 offset:21504
	ds_read_b128 v[212:215], v152 offset:22528
	ds_read_b128 v[216:219], v152 offset:23552
	global_load_lds_dwordx4 v134, s[34:35]
	s_add_i32 m0, s56, 0x2000
	s_add_u32 s56, s34, 0x100000
	s_addc_u32 s57, s35, 0
	s_add_i32 s58, s48, s33
	global_load_lds_dwordx4 v130, s[34:35]
	s_mov_b32 m0, s58
	s_nop 0
	global_load_lds_dwordx4 v134, s[56:57]
	s_add_i32 m0, s58, 0x2000
	s_nop 0
	global_load_lds_dwordx4 v130, s[56:57]
	s_waitcnt vmcnt(6)
	s_waitcnt lgkmcnt(0)
	s_barrier
	v_mfma_f32_16x16x32_bf16 v[62:65], v[154:157], v[186:189], v[62:65]
	v_mfma_f32_16x16x32_bf16 v[58:61], v[162:165], v[186:189], v[58:61]
	v_mfma_f32_16x16x32_bf16 v[46:49], v[154:157], v[194:197], v[46:49]
	v_mfma_f32_16x16x32_bf16 v[42:45], v[162:165], v[194:197], v[42:45]
	v_mfma_f32_16x16x32_bf16 v[30:33], v[154:157], v[204:207], v[30:33]
	v_mfma_f32_16x16x32_bf16 v[26:29], v[162:165], v[204:207], v[26:29]
	v_mfma_f32_16x16x32_bf16 v[14:17], v[154:157], v[212:215], v[14:17]
	v_mfma_f32_16x16x32_bf16 v[10:13], v[162:165], v[212:215], v[10:13]
	v_mfma_f32_16x16x32_bf16 v[62:65], v[158:161], v[190:193], v[62:65]
	v_mfma_f32_16x16x32_bf16 v[58:61], v[166:169], v[190:193], v[58:61]
	v_mfma_f32_16x16x32_bf16 v[46:49], v[158:161], v[200:203], v[46:49]
	v_mfma_f32_16x16x32_bf16 v[42:45], v[166:169], v[200:203], v[42:45]
	v_mfma_f32_16x16x32_bf16 v[30:33], v[158:161], v[208:211], v[30:33]
	v_mfma_f32_16x16x32_bf16 v[26:29], v[166:169], v[208:211], v[26:29]
	v_mfma_f32_16x16x32_bf16 v[14:17], v[158:161], v[216:219], v[14:17]
	v_mfma_f32_16x16x32_bf16 v[10:13], v[166:169], v[216:219], v[10:13]
	v_mfma_f32_16x16x32_bf16 v[54:57], v[170:173], v[186:189], v[54:57]
	v_mfma_f32_16x16x32_bf16 v[50:53], v[178:181], v[186:189], v[50:53]
	v_mfma_f32_16x16x32_bf16 v[38:41], v[170:173], v[194:197], v[38:41]
	v_mfma_f32_16x16x32_bf16 v[34:37], v[178:181], v[194:197], v[34:37]
	v_mfma_f32_16x16x32_bf16 v[22:25], v[170:173], v[204:207], v[22:25]
	v_mfma_f32_16x16x32_bf16 v[18:21], v[178:181], v[204:207], v[18:21]
	v_mfma_f32_16x16x32_bf16 v[6:9], v[170:173], v[212:215], v[6:9]
	v_mfma_f32_16x16x32_bf16 v[2:5], v[178:181], v[212:215], v[2:5]
	v_mfma_f32_16x16x32_bf16 v[54:57], v[174:177], v[190:193], v[54:57]
	v_mfma_f32_16x16x32_bf16 v[50:53], v[182:185], v[190:193], v[50:53]
	v_mfma_f32_16x16x32_bf16 v[38:41], v[174:177], v[200:203], v[38:41]
	v_mfma_f32_16x16x32_bf16 v[34:37], v[182:185], v[200:203], v[34:37]
	v_mfma_f32_16x16x32_bf16 v[22:25], v[174:177], v[208:211], v[22:25]
	v_mfma_f32_16x16x32_bf16 v[18:21], v[182:185], v[208:211], v[18:21]
	v_mfma_f32_16x16x32_bf16 v[6:9], v[174:177], v[216:219], v[6:9]
	v_mfma_f32_16x16x32_bf16 v[2:5], v[182:185], v[216:219], v[2:5]
	s_barrier
; #define PG8_STAGE(bufoff, gbase, voff) do { _Pragma("unroll") for (int _i = 0; _i < 2; ++_i) \
;         __builtin_amdgcn_global_load_lds((const unsigned*)((const char*)(gbase) + (voff)[_i]), (PG8_LAS unsigned*)(lds + (bufoff) + ldsw + _i * 8192), 16, 0, 0); } while (0)
; #define PG8_LDA(dst, b, h) do { _Pragma("unroll") for (int m = 0; m < 4; ++m) _Pragma("unroll") for (int k = 0; k < 2; ++k) dst[m][k] = *(const PG8_LAS bf16x8*)(lds + PG8_SA(b, h) + aoff + m * 2048 + k * 1024); } while (0)
; #define PG8_LDB(dst, b, h) do { _Pragma("unroll") for (int n = 0; n < 2; ++n) _Pragma("unroll") for (int k = 0; k < 2; ++k) dst[n][k] = *(const PG8_LAS bf16x8*)(lds + PG8_SB(b, h) + boff + n * 2048 + k * 1024); } while (0)
; #define PG8_MMA(ai, bj, At, Bt) do { __builtin_amdgcn_s_setprio(1); _Pragma("unroll") for (int m = 0; m < 4; ++m) _Pragma("unroll") for (int n = 0; n < 2; ++n) _Pragma("unroll") for (int k = 0; k < 2; ++k) \
;         acc[ai][bj][m][n] = __builtin_amdgcn_mfma_f32_16x16x32_bf16(Bt[n][k], At[m][k], acc[ai][bj][m][n], 0, 0, 0); __builtin_amdgcn_s_setprio(0); } while (0)
; #define PG8_WAIT_V(n) asm volatile("s_waitcnt vmcnt(" #n ")" ::: "memory")
; #define PG8_WAIT_L(n) asm volatile("s_waitcnt lgkmcnt(" #n ")" ::: "memory")
; #define PG8_BAR __builtin_amdgcn_s_barrier()
; #define PG8_SCHED __builtin_amdgcn_sched_barrier(0)
; template <class Epi, class Sched, bool ALIGN_EPI = false, bool SP2 = false>
; __device__ __forceinline__ void gemm_phase(PG8_LAS unsigned char* lds, const Gemm g, const Sched& S, const Epi& E) {
;     ...
;         for (int t = 0; t < nt; t += 2) {
;             const bool last = (t == nt - 2);
;             const char* a1 = cA + (size_t)(t + 1) * kstep;
;             const char* a2 = last ? nA : cA + (size_t)(t + 2) * kstep; const char* b2 = last ? nB : cB + (size_t)(t + 2) * kstep;
;     ...
;             PG8_LDB(B0, 1, 0); PG8_LDB(B1, 1, 1); PG8_SCHED; PG8_LDA(At, 1, 0); PG8_STAGE(PG8_SA(0, 1), a2 + hstep, voffA);
;             PG8_WAIT_V(8); PG8_WAIT_L(0); PG8_BAR; PG8_MMA(0, 0, At, B0); PG8_MMA(0, 1, At, B1); PG8_BAR; PG8_SCHED;
;             PG8_LDA(At, 1, 1); PG8_STAGE(PG8_SB(1, 0), b3, voffB); PG8_STAGE(PG8_SB(1, 1), b3 + hstep, voffB); PG8_STAGE(PG8_SA(1, 0), a3, voffA);
;             PG8_WAIT_V(8); PG8_WAIT_L(0); PG8_BAR; PG8_MMA(1, 0, At, B0); PG8_MMA(1, 1, At, B1); PG8_BAR; PG8_SCHED;
	s_mov_b32 m0, s29
	s_nop 0
	global_load_lds_dwordx4 v136, s[36:37]
	s_mov_b32 m0, s40
	s_nop 0
	global_load_lds_dwordx4 v132, s[36:37]
	s_add_i32 s56, 0, 0x18000
	v_add_u32_e32 v153, s56, v148
	s_add_i32 s57, 0, 0x1c000
	ds_read_b128 v[154:157], v153
	ds_read_b128 v[158:161], v153 offset:1024
	ds_read_b128 v[162:165], v153 offset:2048
	ds_read_b128 v[166:169], v153 offset:3072
	v_add_u32_e32 v153, s57, v148
	ds_read_b128 v[170:173], v153
	ds_read_b128 v[174:177], v153 offset:1024
	ds_read_b128 v[178:181], v153 offset:2048
	ds_read_b128 v[182:185], v153 offset:3072
	s_add_u32 s36, s36, 0x100000
	s_addc_u32 s37, s37, 0
	s_mov_b32 m0, s41
	ds_read_b128 v[186:189], v152 offset:32768
	ds_read_b128 v[190:193], v152 offset:33792
	ds_read_b128 v[194:197], v152 offset:34816
	ds_read_b128 v[200:203], v152 offset:35840
	ds_read_b128 v[204:207], v152 offset:36864
	ds_read_b128 v[208:211], v152 offset:37888
	ds_read_b128 v[212:215], v152 offset:38912
	ds_read_b128 v[216:219], v152 offset:39936
	global_load_lds_dwordx4 v136, s[36:37]
	s_mov_b32 m0, s42
	s_nop 0
	global_load_lds_dwordx4 v132, s[36:37]
	s_waitcnt vmcnt(8)
	s_waitcnt lgkmcnt(0)
	s_barrier
	v_mfma_f32_16x16x32_bf16 v[126:129], v[154:157], v[186:189], v[126:129]
	v_mfma_f32_16x16x32_bf16 v[122:125], v[162:165], v[186:189], v[122:125]
	v_mfma_f32_16x16x32_bf16 v[110:113], v[154:157], v[194:197], v[110:113]
	v_mfma_f32_16x16x32_bf16 v[106:109], v[162:165], v[194:197], v[106:109]
	v_mfma_f32_16x16x32_bf16 v[94:97], v[154:157], v[204:207], v[94:97]
	v_mfma_f32_16x16x32_bf16 v[90:93], v[162:165], v[204:207], v[90:93]
	v_mfma_f32_16x16x32_bf16 v[78:81], v[154:157], v[212:215], v[78:81]
	v_mfma_f32_16x16x32_bf16 v[74:77], v[162:165], v[212:215], v[74:77]
	v_mfma_f32_16x16x32_bf16 v[126:129], v[158:161], v[190:193], v[126:129]
	v_mfma_f32_16x16x32_bf16 v[122:125], v[166:169], v[190:193], v[122:125]
	v_mfma_f32_16x16x32_bf16 v[110:113], v[158:161], v[200:203], v[110:113]
	v_mfma_f32_16x16x32_bf16 v[106:109], v[166:169], v[200:203], v[106:109]
	v_mfma_f32_16x16x32_bf16 v[94:97], v[158:161], v[208:211], v[94:97]
	v_mfma_f32_16x16x32_bf16 v[90:93], v[166:169], v[208:211], v[90:93]
	v_mfma_f32_16x16x32_bf16 v[78:81], v[158:161], v[216:219], v[78:81]
	v_mfma_f32_16x16x32_bf16 v[74:77], v[166:169], v[216:219], v[74:77]
	v_mfma_f32_16x16x32_bf16 v[118:121], v[170:173], v[186:189], v[118:121]
	v_mfma_f32_16x16x32_bf16 v[114:117], v[178:181], v[186:189], v[114:117]
	v_mfma_f32_16x16x32_bf16 v[102:105], v[170:173], v[194:197], v[102:105]
	v_mfma_f32_16x16x32_bf16 v[98:101], v[178:181], v[194:197], v[98:101]
	v_mfma_f32_16x16x32_bf16 v[86:89], v[170:173], v[204:207], v[86:89]
	v_mfma_f32_16x16x32_bf16 v[82:85], v[178:181], v[204:207], v[82:85]
	v_mfma_f32_16x16x32_bf16 v[70:73], v[170:173], v[212:215], v[70:73]
	v_mfma_f32_16x16x32_bf16 v[66:69], v[178:181], v[212:215], v[66:69]
	v_mfma_f32_16x16x32_bf16 v[118:121], v[174:177], v[190:193], v[118:121]
	v_mfma_f32_16x16x32_bf16 v[114:117], v[182:185], v[190:193], v[114:117]
	v_mfma_f32_16x16x32_bf16 v[102:105], v[174:177], v[200:203], v[102:105]
	v_mfma_f32_16x16x32_bf16 v[98:101], v[182:185], v[200:203], v[98:101]
	v_mfma_f32_16x16x32_bf16 v[86:89], v[174:177], v[208:211], v[86:89]
	v_mfma_f32_16x16x32_bf16 v[82:85], v[182:185], v[208:211], v[82:85]
	v_mfma_f32_16x16x32_bf16 v[70:73], v[174:177], v[216:219], v[70:73]
	v_mfma_f32_16x16x32_bf16 v[66:69], v[182:185], v[216:219], v[66:69]
	s_barrier
	s_add_i32 s36, s56, s33
	s_add_u32 s34, s34, 0x80
	s_addc_u32 s35, s35, 0
	s_mov_b32 m0, s36
	ds_read_b128 v[186:189], v152 offset:49152
	ds_read_b128 v[190:193], v152 offset:50176
	ds_read_b128 v[194:197], v152 offset:51200
	ds_read_b128 v[200:203], v152 offset:52224
	ds_read_b128 v[204:207], v152 offset:53248
	ds_read_b128 v[208:211], v152 offset:54272
	ds_read_b128 v[212:215], v152 offset:55296
	ds_read_b128 v[216:219], v152 offset:56320
	global_load_lds_dwordx4 v134, s[34:35]
	s_add_i32 m0, s36, 0x2000
	s_add_i32 s36, s57, s33
	global_load_lds_dwordx4 v130, s[34:35]
	s_add_u32 s34, s34, 0x100000
	s_addc_u32 s35, s35, 0
	s_mov_b32 m0, s36
	s_nop 0
	global_load_lds_dwordx4 v134, s[34:35]
	s_add_i32 m0, s36, 0x2000
	s_nop 0
	global_load_lds_dwordx4 v130, s[34:35]
	s_waitcnt vmcnt(6)
	s_waitcnt lgkmcnt(0)
	s_barrier
	v_mfma_f32_16x16x32_bf16 v[62:65], v[154:157], v[186:189], v[62:65]
	v_mfma_f32_16x16x32_bf16 v[58:61], v[162:165], v[186:189], v[58:61]
	v_mfma_f32_16x16x32_bf16 v[46:49], v[154:157], v[194:197], v[46:49]
	v_mfma_f32_16x16x32_bf16 v[42:45], v[162:165], v[194:197], v[42:45]
	v_mfma_f32_16x16x32_bf16 v[30:33], v[154:157], v[204:207], v[30:33]
	v_mfma_f32_16x16x32_bf16 v[26:29], v[162:165], v[204:207], v[26:29]
	v_mfma_f32_16x16x32_bf16 v[14:17], v[154:157], v[212:215], v[14:17]
	v_mfma_f32_16x16x32_bf16 v[10:13], v[162:165], v[212:215], v[10:13]
	v_mfma_f32_16x16x32_bf16 v[62:65], v[158:161], v[190:193], v[62:65]
	v_mfma_f32_16x16x32_bf16 v[58:61], v[166:169], v[190:193], v[58:61]
	v_mfma_f32_16x16x32_bf16 v[46:49], v[158:161], v[200:203], v[46:49]
	v_mfma_f32_16x16x32_bf16 v[42:45], v[166:169], v[200:203], v[42:45]
	v_mfma_f32_16x16x32_bf16 v[30:33], v[158:161], v[208:211], v[30:33]
	v_mfma_f32_16x16x32_bf16 v[26:29], v[166:169], v[208:211], v[26:29]
	v_mfma_f32_16x16x32_bf16 v[14:17], v[158:161], v[216:219], v[14:17]
	v_mfma_f32_16x16x32_bf16 v[10:13], v[166:169], v[216:219], v[10:13]
	v_mfma_f32_16x16x32_bf16 v[54:57], v[170:173], v[186:189], v[54:57]
	v_mfma_f32_16x16x32_bf16 v[50:53], v[178:181], v[186:189], v[50:53]
	v_mfma_f32_16x16x32_bf16 v[38:41], v[170:173], v[194:197], v[38:41]
	v_mfma_f32_16x16x32_bf16 v[34:37], v[178:181], v[194:197], v[34:37]
	v_mfma_f32_16x16x32_bf16 v[22:25], v[170:173], v[204:207], v[22:25]
	v_mfma_f32_16x16x32_bf16 v[18:21], v[178:181], v[204:207], v[18:21]
	v_mfma_f32_16x16x32_bf16 v[6:9], v[170:173], v[212:215], v[6:9]
	v_mfma_f32_16x16x32_bf16 v[2:5], v[178:181], v[212:215], v[2:5]
	v_mfma_f32_16x16x32_bf16 v[54:57], v[174:177], v[190:193], v[54:57]
	v_mfma_f32_16x16x32_bf16 v[50:53], v[182:185], v[190:193], v[50:53]
	v_mfma_f32_16x16x32_bf16 v[38:41], v[174:177], v[200:203], v[38:41]
	v_mfma_f32_16x16x32_bf16 v[34:37], v[182:185], v[200:203], v[34:37]
	v_mfma_f32_16x16x32_bf16 v[22:25], v[174:177], v[208:211], v[22:25]
	v_mfma_f32_16x16x32_bf16 v[18:21], v[182:185], v[208:211], v[18:21]
	v_mfma_f32_16x16x32_bf16 v[6:9], v[174:177], v[216:219], v[6:9]
	v_mfma_f32_16x16x32_bf16 v[2:5], v[182:185], v[216:219], v[2:5]
	s_barrier
	s_add_i32 s55, s55, 2
	s_add_u32 s30, s30, 0x100
	s_addc_u32 s31, s31, 0
	s_add_u32 s53, s53, 0x100
	s_addc_u32 s54, s54, 0
	s_cmp_gt_u32 s55, 61
	s_cbranch_scc0 .LBB0_1081
	s_and_b64 vcc, exec, s[10:11]
	s_cbranch_vccz .LBB0_1084
	s_barrier

; #define PG8_STAGE(bufoff, gbase, voff) do { _Pragma("unroll") for (int _i = 0; _i < 2; ++_i) \
;         __builtin_amdgcn_global_load_lds((const unsigned*)((const char*)(gbase) + (voff)[_i]), (PG8_LAS unsigned*)(lds + (bufoff) + ldsw + _i * 8192), 16, 0, 0); } while (0)
; #define PG8_LDA(dst, b, h) do { _Pragma("unroll") for (int m = 0; m < 4; ++m) _Pragma("unroll") for (int k = 0; k < 2; ++k) dst[m][k] = *(const PG8_LAS bf16x8*)(lds + PG8_SA(b, h) + aoff + m * 2048 + k * 1024); } while (0)
; #define PG8_LDB(dst, b, h) do { _Pragma("unroll") for (int n = 0; n < 2; ++n) _Pragma("unroll") for (int k = 0; k < 2; ++k) dst[n][k] = *(const PG8_LAS bf16x8*)(lds + PG8_SB(b, h) + boff + n * 2048 + k * 1024); } while (0)
; #define PG8_MMA(ai, bj, At, Bt) do { __builtin_amdgcn_s_setprio(1); _Pragma("unroll") for (int m = 0; m < 4; ++m) _Pragma("unroll") for (int n = 0; n < 2; ++n) _Pragma("unroll") for (int k = 0; k < 2; ++k) \
;         acc[ai][bj][m][n] = __builtin_amdgcn_mfma_f32_16x16x32_bf16(Bt[n][k], At[m][k], acc[ai][bj][m][n], 0, 0, 0); __builtin_amdgcn_s_setprio(0); } while (0)
; #define PG8_WAIT_V(n) asm volatile("s_waitcnt vmcnt(" #n ")" ::: "memory")
; #define PG8_WAIT_L(n) asm volatile("s_waitcnt lgkmcnt(" #n ")" ::: "memory")
; #define PG8_BAR __builtin_amdgcn_s_barrier()
; #define PG8_SCHED __builtin_amdgcn_sched_barrier(0)
; template <class Epi, class Sched, bool ALIGN_EPI = false, bool SP2 = false>
; __device__ __forceinline__ void gemm_phase(PG8_LAS unsigned char* lds, const Gemm g, const Sched& S, const Epi& E) {
;     ...
;             PG8_LDB(B0, 0, 0); PG8_LDB(B1, 0, 1); PG8_SCHED; PG8_LDA(At, 0, 0); PG8_STAGE(PG8_SA(1, 1), a1 + hstep, voffA);
;             PG8_WAIT_V(8); PG8_WAIT_L(0); PG8_BAR; PG8_MMA(0, 0, At, B0); PG8_MMA(0, 1, At, B1); PG8_BAR; PG8_SCHED;
;             PG8_LDA(At, 0, 1); PG8_STAGE(PG8_SB(0, 0), b2, voffB); PG8_STAGE(PG8_SB(0, 1), b2 + hstep, voffB); PG8_STAGE(PG8_SA(0, 0), a2, voffA);
;             PG8_WAIT_V(8); PG8_WAIT_L(0); PG8_BAR; PG8_MMA(1, 0, At, B0); PG8_MMA(1, 1, At, B1); PG8_BAR; PG8_SCHED;
.LBB0_1164:
	s_add_u32 s16, s14, 0xffd50000
	s_addc_u32 s17, s15, -1
	s_mov_b32 m0, s29
	s_nop 0
	global_load_lds_dwordx4 v128, s[16:17]
	s_mov_b32 m0, s30
	s_nop 0
	global_load_lds_dwordx4 v130, s[16:17]
	s_add_u32 s16, s16, 0x80
	s_addc_u32 s17, s17, 0
	ds_read_b128 v[140:143], v193
	ds_read_b128 v[144:147], v193 offset:1024
	ds_read_b128 v[148:151], v193 offset:2048
	ds_read_b128 v[152:155], v193 offset:3072
	ds_read_b128 v[156:159], v194
	ds_read_b128 v[160:163], v194 offset:1024
	ds_read_b128 v[164:167], v194 offset:2048
	ds_read_b128 v[168:171], v194 offset:3072
	s_cmpk_eq_i32 s41, 0xa8
	s_cselect_b32 s21, s5, s17
	s_cselect_b32 s20, s4, s16
	s_cselect_b32 s17, s13, s40
	s_cselect_b32 s16, s12, s39
	s_add_i32 m0, s24, 0xc000
	ds_read_b128 v[172:175], v195
	ds_read_b128 v[176:179], v195 offset:1024
	ds_read_b128 v[180:183], v195 offset:2048
	ds_read_b128 v[184:187], v195 offset:3072
	ds_read_b128 v[196:199], v195 offset:4096
	ds_read_b128 v[200:203], v195 offset:5120
	ds_read_b128 v[204:207], v195 offset:6144
	ds_read_b128 v[208:211], v195 offset:7168
	global_load_lds_dwordx4 v132, s[14:15]
	s_add_i32 m0, s24, 0xe000
	s_nop 0
	global_load_lds_dwordx4 v134, s[14:15]
	s_waitcnt vmcnt(8)
	s_waitcnt lgkmcnt(0)
	s_barrier
	v_mfma_f32_16x16x32_bf16 v[124:127], v[140:143], v[172:175], v[124:127]
	v_mfma_f32_16x16x32_bf16 v[120:123], v[148:151], v[172:175], v[120:123]
	v_mfma_f32_16x16x32_bf16 v[112:115], v[140:143], v[180:183], v[112:115]
	v_mfma_f32_16x16x32_bf16 v[104:107], v[148:151], v[180:183], v[104:107]
	v_mfma_f32_16x16x32_bf16 v[96:99], v[140:143], v[196:199], v[96:99]
	v_mfma_f32_16x16x32_bf16 v[88:91], v[148:151], v[196:199], v[88:91]
	v_mfma_f32_16x16x32_bf16 v[80:83], v[140:143], v[204:207], v[80:83]
	v_mfma_f32_16x16x32_bf16 v[72:75], v[148:151], v[204:207], v[72:75]
	v_mfma_f32_16x16x32_bf16 v[124:127], v[144:147], v[176:179], v[124:127]
	v_mfma_f32_16x16x32_bf16 v[120:123], v[152:155], v[176:179], v[120:123]
	v_mfma_f32_16x16x32_bf16 v[112:115], v[144:147], v[184:187], v[112:115]
	v_mfma_f32_16x16x32_bf16 v[104:107], v[152:155], v[184:187], v[104:107]
	v_mfma_f32_16x16x32_bf16 v[96:99], v[144:147], v[200:203], v[96:99]
	v_mfma_f32_16x16x32_bf16 v[88:91], v[152:155], v[200:203], v[88:91]
	v_mfma_f32_16x16x32_bf16 v[80:83], v[144:147], v[208:211], v[80:83]
	v_mfma_f32_16x16x32_bf16 v[72:75], v[152:155], v[208:211], v[72:75]
	v_mfma_f32_16x16x32_bf16 v[116:119], v[156:159], v[172:175], v[116:119]
	v_mfma_f32_16x16x32_bf16 v[108:111], v[164:167], v[172:175], v[108:111]
	v_mfma_f32_16x16x32_bf16 v[100:103], v[156:159], v[180:183], v[100:103]
	v_mfma_f32_16x16x32_bf16 v[92:95], v[164:167], v[180:183], v[92:95]
	v_mfma_f32_16x16x32_bf16 v[84:87], v[156:159], v[196:199], v[84:87]
	v_mfma_f32_16x16x32_bf16 v[76:79], v[164:167], v[196:199], v[76:79]
	v_mfma_f32_16x16x32_bf16 v[68:71], v[156:159], v[204:207], v[68:71]
	v_mfma_f32_16x16x32_bf16 v[64:67], v[164:167], v[204:207], v[64:67]
	v_mfma_f32_16x16x32_bf16 v[116:119], v[160:163], v[176:179], v[116:119]
	v_mfma_f32_16x16x32_bf16 v[108:111], v[168:171], v[176:179], v[108:111]
	v_mfma_f32_16x16x32_bf16 v[100:103], v[160:163], v[184:187], v[100:103]
	v_mfma_f32_16x16x32_bf16 v[92:95], v[168:171], v[184:187], v[92:95]
	v_mfma_f32_16x16x32_bf16 v[84:87], v[160:163], v[200:203], v[84:87]
	v_mfma_f32_16x16x32_bf16 v[76:79], v[168:171], v[200:203], v[76:79]
	v_mfma_f32_16x16x32_bf16 v[68:71], v[160:163], v[208:211], v[68:71]
	v_mfma_f32_16x16x32_bf16 v[64:67], v[168:171], v[208:211], v[64:67]
	s_barrier
	s_add_i32 s42, s33, s23
	s_mov_b32 m0, s42
	ds_read_b128 v[172:175], v195 offset:16384
	ds_read_b128 v[176:179], v195 offset:17408
	ds_read_b128 v[180:183], v195 offset:18432
	ds_read_b128 v[184:187], v195 offset:19456
	ds_read_b128 v[196:199], v195 offset:20480
	ds_read_b128 v[200:203], v195 offset:21504
	ds_read_b128 v[204:207], v195 offset:22528
	ds_read_b128 v[208:211], v195 offset:23552
	global_load_lds_dwordx4 v128, s[16:17]
	s_add_i32 m0, s42, 0x2000
	s_add_u32 s42, s16, 0x2b0000
	s_addc_u32 s43, s17, 0
	s_add_i32 s44, s34, s23
	global_load_lds_dwordx4 v130, s[16:17]
	s_mov_b32 m0, s44
	s_nop 0
	global_load_lds_dwordx4 v128, s[42:43]
	s_add_i32 m0, s44, 0x2000
	s_nop 0
	global_load_lds_dwordx4 v130, s[42:43]
	s_waitcnt vmcnt(6)
	s_waitcnt lgkmcnt(0)
	s_barrier
	v_mfma_f32_16x16x32_bf16 v[60:63], v[140:143], v[172:175], v[60:63]
	v_mfma_f32_16x16x32_bf16 v[56:59], v[148:151], v[172:175], v[56:59]
	v_mfma_f32_16x16x32_bf16 v[48:51], v[140:143], v[180:183], v[48:51]
	v_mfma_f32_16x16x32_bf16 v[40:43], v[148:151], v[180:183], v[40:43]
	v_mfma_f32_16x16x32_bf16 v[32:35], v[140:143], v[196:199], v[32:35]
	v_mfma_f32_16x16x32_bf16 v[24:27], v[148:151], v[196:199], v[24:27]
	v_mfma_f32_16x16x32_bf16 v[16:19], v[140:143], v[204:207], v[16:19]
	v_mfma_f32_16x16x32_bf16 v[8:11], v[148:151], v[204:207], v[8:11]
	v_mfma_f32_16x16x32_bf16 v[60:63], v[144:147], v[176:179], v[60:63]
	v_mfma_f32_16x16x32_bf16 v[56:59], v[152:155], v[176:179], v[56:59]
	v_mfma_f32_16x16x32_bf16 v[48:51], v[144:147], v[184:187], v[48:51]
	v_mfma_f32_16x16x32_bf16 v[40:43], v[152:155], v[184:187], v[40:43]
	v_mfma_f32_16x16x32_bf16 v[32:35], v[144:147], v[200:203], v[32:35]
	v_mfma_f32_16x16x32_bf16 v[24:27], v[152:155], v[200:203], v[24:27]
	v_mfma_f32_16x16x32_bf16 v[16:19], v[144:147], v[208:211], v[16:19]
	v_mfma_f32_16x16x32_bf16 v[8:11], v[152:155], v[208:211], v[8:11]
	v_mfma_f32_16x16x32_bf16 v[52:55], v[156:159], v[172:175], v[52:55]
	v_mfma_f32_16x16x32_bf16 v[44:47], v[164:167], v[172:175], v[44:47]
	v_mfma_f32_16x16x32_bf16 v[36:39], v[156:159], v[180:183], v[36:39]
	v_mfma_f32_16x16x32_bf16 v[28:31], v[164:167], v[180:183], v[28:31]
	v_mfma_f32_16x16x32_bf16 v[20:23], v[156:159], v[196:199], v[20:23]
	v_mfma_f32_16x16x32_bf16 v[12:15], v[164:167], v[196:199], v[12:15]
	v_mfma_f32_16x16x32_bf16 v[4:7], v[156:159], v[204:207], v[4:7]
	v_mfma_f32_16x16x32_bf16 v[0:3], v[164:167], v[204:207], v[0:3]
	v_mfma_f32_16x16x32_bf16 v[52:55], v[160:163], v[176:179], v[52:55]
	v_mfma_f32_16x16x32_bf16 v[44:47], v[168:171], v[176:179], v[44:47]
	v_mfma_f32_16x16x32_bf16 v[36:39], v[160:163], v[184:187], v[36:39]
	v_mfma_f32_16x16x32_bf16 v[28:31], v[168:171], v[184:187], v[28:31]
	v_mfma_f32_16x16x32_bf16 v[20:23], v[160:163], v[200:203], v[20:23]
	v_mfma_f32_16x16x32_bf16 v[12:15], v[168:171], v[200:203], v[12:15]
	v_mfma_f32_16x16x32_bf16 v[4:7], v[160:163], v[208:211], v[4:7]
	v_mfma_f32_16x16x32_bf16 v[0:3], v[168:171], v[208:211], v[0:3]
	s_barrier
; #define PG8_STAGE(bufoff, gbase, voff) do { _Pragma("unroll") for (int _i = 0; _i < 2; ++_i) \
;         __builtin_amdgcn_global_load_lds((const unsigned*)((const char*)(gbase) + (voff)[_i]), (PG8_LAS unsigned*)(lds + (bufoff) + ldsw + _i * 8192), 16, 0, 0); } while (0)
; #define PG8_LDA(dst, b, h) do { _Pragma("unroll") for (int m = 0; m < 4; ++m) _Pragma("unroll") for (int k = 0; k < 2; ++k) dst[m][k] = *(const PG8_LAS bf16x8*)(lds + PG8_SA(b, h) + aoff + m * 2048 + k * 1024); } while (0)
; #define PG8_LDB(dst, b, h) do { _Pragma("unroll") for (int n = 0; n < 2; ++n) _Pragma("unroll") for (int k = 0; k < 2; ++k) dst[n][k] = *(const PG8_LAS bf16x8*)(lds + PG8_SB(b, h) + boff + n * 2048 + k * 1024); } while (0)
; #define PG8_MMA(ai, bj, At, Bt) do { __builtin_amdgcn_s_setprio(1); _Pragma("unroll") for (int m = 0; m < 4; ++m) _Pragma("unroll") for (int n = 0; n < 2; ++n) _Pragma("unroll") for (int k = 0; k < 2; ++k) \
;         acc[ai][bj][m][n] = __builtin_amdgcn_mfma_f32_16x16x32_bf16(Bt[n][k], At[m][k], acc[ai][bj][m][n], 0, 0, 0); __builtin_amdgcn_s_setprio(0); } while (0)
; #define PG8_WAIT_V(n) asm volatile("s_waitcnt vmcnt(" #n ")" ::: "memory")
; #define PG8_WAIT_L(n) asm volatile("s_waitcnt lgkmcnt(" #n ")" ::: "memory")
; #define PG8_BAR __builtin_amdgcn_s_barrier()
; #define PG8_SCHED __builtin_amdgcn_sched_barrier(0)
; template <class Epi, class Sched, bool ALIGN_EPI = false, bool SP2 = false>
; __device__ __forceinline__ void gemm_phase(PG8_LAS unsigned char* lds, const Gemm g, const Sched& S, const Epi& E) {
;     ...
;         for (int t = 0; t < nt; t += 2) {
;             const bool last = (t == nt - 2);
;             const char* a1 = cA + (size_t)(t + 1) * kstep;
;             const char* a2 = last ? nA : cA + (size_t)(t + 2) * kstep; const char* b2 = last ? nB : cB + (size_t)(t + 2) * kstep;
;     ...
;             PG8_LDB(B0, 1, 0); PG8_LDB(B1, 1, 1); PG8_SCHED; PG8_LDA(At, 1, 0); PG8_STAGE(PG8_SA(0, 1), a2 + hstep, voffA);
;             PG8_WAIT_V(8); PG8_WAIT_L(0); PG8_BAR; PG8_MMA(0, 0, At, B0); PG8_MMA(0, 1, At, B1); PG8_BAR; PG8_SCHED;
;             PG8_LDA(At, 1, 1); PG8_STAGE(PG8_SB(1, 0), b3, voffB); PG8_STAGE(PG8_SB(1, 1), b3 + hstep, voffB); PG8_STAGE(PG8_SA(1, 0), a3, voffA);
;             PG8_WAIT_V(8); PG8_WAIT_L(0); PG8_BAR; PG8_MMA(1, 0, At, B0); PG8_MMA(1, 1, At, B1); PG8_BAR; PG8_SCHED;
	s_mov_b32 m0, s24
	s_nop 0
	global_load_lds_dwordx4 v128, s[20:21]
	s_mov_b32 m0, s25
	s_nop 0
	global_load_lds_dwordx4 v130, s[20:21]
	s_add_i32 s42, 0, 0x18000
	s_add_i32 s43, 0, 0x1c000
	v_add_u32_e32 v152, s42, v191
	v_add_u32_e32 v168, s43, v191
	ds_read_b128 v[140:143], v152
	ds_read_b128 v[144:147], v152 offset:1024
	ds_read_b128 v[148:151], v152 offset:2048
	ds_read_b128 v[152:155], v152 offset:3072
	ds_read_b128 v[156:159], v168
	ds_read_b128 v[160:163], v168 offset:1024
	ds_read_b128 v[164:167], v168 offset:2048
	ds_read_b128 v[168:171], v168 offset:3072
	s_add_u32 s20, s20, 0x2b0000
	s_addc_u32 s21, s21, 0
	s_mov_b32 m0, s26
	ds_read_b128 v[172:175], v195 offset:32768
	ds_read_b128 v[176:179], v195 offset:33792
	ds_read_b128 v[180:183], v195 offset:34816
	ds_read_b128 v[184:187], v195 offset:35840
	ds_read_b128 v[196:199], v195 offset:36864
	ds_read_b128 v[200:203], v195 offset:37888
	ds_read_b128 v[204:207], v195 offset:38912
	ds_read_b128 v[208:211], v195 offset:39936
	global_load_lds_dwordx4 v128, s[20:21]
	s_mov_b32 m0, s27
	s_nop 0
	global_load_lds_dwordx4 v130, s[20:21]
	s_waitcnt vmcnt(8)
	s_waitcnt lgkmcnt(0)
	s_barrier
	v_mfma_f32_16x16x32_bf16 v[124:127], v[140:143], v[172:175], v[124:127]
	v_mfma_f32_16x16x32_bf16 v[120:123], v[148:151], v[172:175], v[120:123]
	v_mfma_f32_16x16x32_bf16 v[112:115], v[140:143], v[180:183], v[112:115]
	v_mfma_f32_16x16x32_bf16 v[104:107], v[148:151], v[180:183], v[104:107]
	v_mfma_f32_16x16x32_bf16 v[96:99], v[140:143], v[196:199], v[96:99]
	v_mfma_f32_16x16x32_bf16 v[88:91], v[148:151], v[196:199], v[88:91]
	v_mfma_f32_16x16x32_bf16 v[80:83], v[140:143], v[204:207], v[80:83]
	v_mfma_f32_16x16x32_bf16 v[72:75], v[148:151], v[204:207], v[72:75]
	v_mfma_f32_16x16x32_bf16 v[124:127], v[144:147], v[176:179], v[124:127]
	v_mfma_f32_16x16x32_bf16 v[120:123], v[152:155], v[176:179], v[120:123]
	v_mfma_f32_16x16x32_bf16 v[112:115], v[144:147], v[184:187], v[112:115]
	v_mfma_f32_16x16x32_bf16 v[104:107], v[152:155], v[184:187], v[104:107]
	v_mfma_f32_16x16x32_bf16 v[96:99], v[144:147], v[200:203], v[96:99]
	v_mfma_f32_16x16x32_bf16 v[88:91], v[152:155], v[200:203], v[88:91]
	v_mfma_f32_16x16x32_bf16 v[80:83], v[144:147], v[208:211], v[80:83]
	v_mfma_f32_16x16x32_bf16 v[72:75], v[152:155], v[208:211], v[72:75]
	v_mfma_f32_16x16x32_bf16 v[116:119], v[156:159], v[172:175], v[116:119]
	v_mfma_f32_16x16x32_bf16 v[108:111], v[164:167], v[172:175], v[108:111]
	v_mfma_f32_16x16x32_bf16 v[100:103], v[156:159], v[180:183], v[100:103]
	v_mfma_f32_16x16x32_bf16 v[92:95], v[164:167], v[180:183], v[92:95]
	v_mfma_f32_16x16x32_bf16 v[84:87], v[156:159], v[196:199], v[84:87]
	v_mfma_f32_16x16x32_bf16 v[76:79], v[164:167], v[196:199], v[76:79]
	v_mfma_f32_16x16x32_bf16 v[68:71], v[156:159], v[204:207], v[68:71]
	v_mfma_f32_16x16x32_bf16 v[64:67], v[164:167], v[204:207], v[64:67]
	v_mfma_f32_16x16x32_bf16 v[116:119], v[160:163], v[176:179], v[116:119]
	v_mfma_f32_16x16x32_bf16 v[108:111], v[168:171], v[176:179], v[108:111]
	v_mfma_f32_16x16x32_bf16 v[100:103], v[160:163], v[184:187], v[100:103]
	v_mfma_f32_16x16x32_bf16 v[92:95], v[168:171], v[184:187], v[92:95]
	v_mfma_f32_16x16x32_bf16 v[84:87], v[160:163], v[200:203], v[84:87]
	v_mfma_f32_16x16x32_bf16 v[76:79], v[168:171], v[200:203], v[76:79]
	v_mfma_f32_16x16x32_bf16 v[68:71], v[160:163], v[208:211], v[68:71]
	v_mfma_f32_16x16x32_bf16 v[64:67], v[168:171], v[208:211], v[64:67]
	s_barrier
	s_add_i32 s20, s42, s23
	s_add_u32 s16, s16, 0x80
	s_addc_u32 s17, s17, 0
	s_mov_b32 m0, s20
	ds_read_b128 v[172:175], v195 offset:49152
	ds_read_b128 v[176:179], v195 offset:50176
	ds_read_b128 v[180:183], v195 offset:51200
	ds_read_b128 v[184:187], v195 offset:52224
	ds_read_b128 v[196:199], v195 offset:53248
	ds_read_b128 v[200:203], v195 offset:54272
	ds_read_b128 v[204:207], v195 offset:55296
	ds_read_b128 v[208:211], v195 offset:56320
	global_load_lds_dwordx4 v128, s[16:17]
	s_add_i32 m0, s20, 0x2000
	s_add_i32 s20, s43, s23
	global_load_lds_dwordx4 v130, s[16:17]
	s_add_u32 s16, s16, 0x2b0000
	s_addc_u32 s17, s17, 0
	s_mov_b32 m0, s20
	s_nop 0
	global_load_lds_dwordx4 v128, s[16:17]
	s_add_i32 m0, s20, 0x2000
	s_nop 0
	global_load_lds_dwordx4 v130, s[16:17]
	s_waitcnt vmcnt(6)
	s_waitcnt lgkmcnt(0)
	s_barrier
	v_mfma_f32_16x16x32_bf16 v[60:63], v[140:143], v[172:175], v[60:63]
	v_mfma_f32_16x16x32_bf16 v[56:59], v[148:151], v[172:175], v[56:59]
	v_mfma_f32_16x16x32_bf16 v[48:51], v[140:143], v[180:183], v[48:51]
	v_mfma_f32_16x16x32_bf16 v[40:43], v[148:151], v[180:183], v[40:43]
	v_mfma_f32_16x16x32_bf16 v[32:35], v[140:143], v[196:199], v[32:35]
	v_mfma_f32_16x16x32_bf16 v[24:27], v[148:151], v[196:199], v[24:27]
	v_mfma_f32_16x16x32_bf16 v[16:19], v[140:143], v[204:207], v[16:19]
	v_mfma_f32_16x16x32_bf16 v[8:11], v[148:151], v[204:207], v[8:11]
	v_mfma_f32_16x16x32_bf16 v[60:63], v[144:147], v[176:179], v[60:63]
	v_mfma_f32_16x16x32_bf16 v[56:59], v[152:155], v[176:179], v[56:59]
	v_mfma_f32_16x16x32_bf16 v[48:51], v[144:147], v[184:187], v[48:51]
	v_mfma_f32_16x16x32_bf16 v[40:43], v[152:155], v[184:187], v[40:43]
	v_mfma_f32_16x16x32_bf16 v[32:35], v[144:147], v[200:203], v[32:35]
	v_mfma_f32_16x16x32_bf16 v[24:27], v[152:155], v[200:203], v[24:27]
	v_mfma_f32_16x16x32_bf16 v[16:19], v[144:147], v[208:211], v[16:19]
	v_mfma_f32_16x16x32_bf16 v[8:11], v[152:155], v[208:211], v[8:11]
	v_mfma_f32_16x16x32_bf16 v[52:55], v[156:159], v[172:175], v[52:55]
	v_mfma_f32_16x16x32_bf16 v[44:47], v[164:167], v[172:175], v[44:47]
	v_mfma_f32_16x16x32_bf16 v[36:39], v[156:159], v[180:183], v[36:39]
	v_mfma_f32_16x16x32_bf16 v[28:31], v[164:167], v[180:183], v[28:31]
	v_mfma_f32_16x16x32_bf16 v[20:23], v[156:159], v[196:199], v[20:23]
	v_mfma_f32_16x16x32_bf16 v[12:15], v[164:167], v[196:199], v[12:15]
	v_mfma_f32_16x16x32_bf16 v[4:7], v[156:159], v[204:207], v[4:7]
	v_mfma_f32_16x16x32_bf16 v[0:3], v[164:167], v[204:207], v[0:3]
	v_mfma_f32_16x16x32_bf16 v[52:55], v[160:163], v[176:179], v[52:55]
	v_mfma_f32_16x16x32_bf16 v[44:47], v[168:171], v[176:179], v[44:47]
	v_mfma_f32_16x16x32_bf16 v[36:39], v[160:163], v[184:187], v[36:39]
	v_mfma_f32_16x16x32_bf16 v[28:31], v[168:171], v[184:187], v[28:31]
	v_mfma_f32_16x16x32_bf16 v[20:23], v[160:163], v[200:203], v[20:23]
	v_mfma_f32_16x16x32_bf16 v[12:15], v[168:171], v[200:203], v[12:15]
	v_mfma_f32_16x16x32_bf16 v[4:7], v[160:163], v[208:211], v[4:7]
	v_mfma_f32_16x16x32_bf16 v[0:3], v[168:171], v[208:211], v[0:3]
	s_barrier
	s_add_i32 s41, s41, 2
	s_add_u32 s14, s14, 0x100
	s_addc_u32 s15, s15, 0
	s_add_u32 s39, s39, 0x100
	s_addc_u32 s40, s40, 0
	s_cmpk_gt_u32 s41, 0xa9
	s_cbranch_scc0 .LBB0_1164
	s_and_b64 vcc, exec, s[10:11]
	s_cbranch_vccz .LBB0_1167
	s_barrier
